# K-loop MFMA blocks padded to 8-byte instruction alignment (s_nop in the load segment)
# speedup vs baseline: 1.0003x; 1.0003x over previous
.Lg1_nopf:
	s_barrier
	v_mfma_f32_16x16x32_bf16 v[124:127], v[128:131], v[204:207], v[124:127]
	v_mfma_f32_16x16x32_bf16 v[120:123], v[136:139], v[204:207], v[120:123]
	v_mfma_f32_16x16x32_bf16 v[96:99], v[128:131], v[212:215], v[96:99]
	v_mfma_f32_16x16x32_bf16 v[88:91], v[136:139], v[212:215], v[88:91]
	v_mfma_f32_16x16x32_bf16 v[76:79], v[128:131], v[220:223], v[76:79]
	v_mfma_f32_16x16x32_bf16 v[72:75], v[136:139], v[220:223], v[72:75]
	v_mfma_f32_16x16x32_bf16 v[60:63], v[128:131], v[228:231], v[60:63]
	v_mfma_f32_16x16x32_bf16 v[108:111], v[136:139], v[228:231], v[108:111]
	v_mfma_f32_16x16x32_bf16 v[124:127], v[132:135], v[208:211], v[124:127]
	v_mfma_f32_16x16x32_bf16 v[120:123], v[158:161], v[208:211], v[120:123]
	v_mfma_f32_16x16x32_bf16 v[96:99], v[132:135], v[216:219], v[96:99]
	v_mfma_f32_16x16x32_bf16 v[88:91], v[158:161], v[216:219], v[88:91]
	v_mfma_f32_16x16x32_bf16 v[76:79], v[132:135], v[224:227], v[76:79]
	v_mfma_f32_16x16x32_bf16 v[72:75], v[158:161], v[224:227], v[72:75]
	v_mfma_f32_16x16x32_bf16 v[60:63], v[132:135], v[232:235], v[60:63]
	v_mfma_f32_16x16x32_bf16 v[108:111], v[158:161], v[232:235], v[108:111]
	v_mfma_f32_16x16x32_bf16 v[116:119], v[168:171], v[204:207], v[116:119]
	v_mfma_f32_16x16x32_bf16 v[112:115], v[196:199], v[204:207], v[112:115]
	v_mfma_f32_16x16x32_bf16 v[84:87], v[168:171], v[212:215], v[84:87]
	v_mfma_f32_16x16x32_bf16 v[80:83], v[196:199], v[212:215], v[80:83]
	v_mfma_f32_16x16x32_bf16 v[68:71], v[168:171], v[220:223], v[68:71]
	v_mfma_f32_16x16x32_bf16 v[64:67], v[196:199], v[220:223], v[64:67]
	v_mfma_f32_16x16x32_bf16 v[104:107], v[168:171], v[228:231], v[104:107]
	v_mfma_f32_16x16x32_bf16 v[56:59], v[196:199], v[228:231], v[56:59]
	v_mfma_f32_16x16x32_bf16 v[116:119], v[172:175], v[208:211], v[116:119]
	v_mfma_f32_16x16x32_bf16 v[112:115], v[200:203], v[208:211], v[112:115]
	v_mfma_f32_16x16x32_bf16 v[84:87], v[172:175], v[216:219], v[84:87]
	v_mfma_f32_16x16x32_bf16 v[80:83], v[200:203], v[216:219], v[80:83]
	v_mfma_f32_16x16x32_bf16 v[68:71], v[172:175], v[224:227], v[68:71]
	v_mfma_f32_16x16x32_bf16 v[64:67], v[200:203], v[224:227], v[64:67]
	v_mfma_f32_16x16x32_bf16 v[104:107], v[172:175], v[232:235], v[104:107]
	v_mfma_f32_16x16x32_bf16 v[56:59], v[200:203], v[232:235], v[56:59]
	s_barrier
	s_setprio 0
	s_add_i32 s87, s82, s23
	v_lshl_add_u64 v[162:163], s[66:67], 0, v[140:141]
	s_mov_b32 m0, s87
	ds_read_b128 v[204:207], v194 offset:16384
	ds_read_b128 v[208:211], v194 offset:17408
	ds_read_b128 v[212:215], v194 offset:18432
	ds_read_b128 v[216:219], v194 offset:19456
	ds_read_b128 v[220:223], v194 offset:20480
	ds_read_b128 v[224:227], v194 offset:21504
	ds_read_b128 v[228:231], v194 offset:22528
	ds_read_b128 v[232:235], v194 offset:23552
	global_load_lds_dwordx4 v[162:163], off
	s_add_i32 m0, s87, 0x2000
	s_add_u32 s88, s66, 0x40000
	v_lshl_add_u64 v[178:179], s[66:67], 0, v[142:143]
	s_addc_u32 s89, s67, 0
	s_add_i32 s87, s83, s23
	global_load_lds_dwordx4 v[178:179], off
	v_lshl_add_u64 v[184:185], s[88:89], 0, v[140:141]
	s_mov_b32 m0, s87
	v_lshl_add_u64 v[236:237], s[68:69], 0, v[142:143]
	global_load_lds_dwordx4 v[184:185], off
	v_lshl_add_u64 v[184:185], s[88:89], 0, v[142:143]
	s_add_i32 m0, s87, 0x2000
	s_nop 0
	global_load_lds_dwordx4 v[184:185], off
	v_lshl_add_u64 v[184:185], s[68:69], 0, v[140:141]
	s_mov_b32 m0, s70
	s_nop 0
	global_load_lds_dwordx4 v[184:185], off
	s_mov_b32 m0, s71
	s_nop 0
	global_load_lds_dwordx4 v[236:237], off
	s_waitcnt vmcnt(8)
	s_waitcnt lgkmcnt(0)
	s_setprio 1
	s_barrier
	v_mfma_f32_16x16x32_bf16 v[52:55], v[128:131], v[204:207], v[52:55]
	v_mfma_f32_16x16x32_bf16 v[48:51], v[136:139], v[204:207], v[48:51]
	v_mfma_f32_16x16x32_bf16 v[16:19], v[128:131], v[212:215], v[16:19]
	v_mfma_f32_16x16x32_bf16 v[8:11], v[136:139], v[212:215], v[8:11]
	v_mfma_f32_16x16x32_bf16 v[28:31], v[128:131], v[220:223], v[28:31]
	v_mfma_f32_16x16x32_bf16 v[24:27], v[136:139], v[220:223], v[24:27]
	v_mfma_f32_16x16x32_bf16 v[36:39], v[128:131], v[228:231], v[36:39]
	v_mfma_f32_16x16x32_bf16 v[100:103], v[136:139], v[228:231], v[100:103]
	v_mfma_f32_16x16x32_bf16 v[52:55], v[132:135], v[208:211], v[52:55]
	v_mfma_f32_16x16x32_bf16 v[48:51], v[158:161], v[208:211], v[48:51]
	v_mfma_f32_16x16x32_bf16 v[16:19], v[132:135], v[216:219], v[16:19]
	v_mfma_f32_16x16x32_bf16 v[8:11], v[158:161], v[216:219], v[8:11]
	v_mfma_f32_16x16x32_bf16 v[28:31], v[132:135], v[224:227], v[28:31]
	v_mfma_f32_16x16x32_bf16 v[24:27], v[158:161], v[224:227], v[24:27]
	v_mfma_f32_16x16x32_bf16 v[36:39], v[132:135], v[232:235], v[36:39]
	v_mfma_f32_16x16x32_bf16 v[100:103], v[158:161], v[232:235], v[100:103]
	v_mfma_f32_16x16x32_bf16 v[44:47], v[168:171], v[204:207], v[44:47]
	v_mfma_f32_16x16x32_bf16 v[40:43], v[196:199], v[204:207], v[40:43]
	v_mfma_f32_16x16x32_bf16 v[0:3], v[168:171], v[212:215], v[0:3]
	v_mfma_f32_16x16x32_bf16 v[4:7], v[196:199], v[212:215], v[4:7]
	v_mfma_f32_16x16x32_bf16 v[12:15], v[168:171], v[220:223], v[12:15]
	v_mfma_f32_16x16x32_bf16 v[20:23], v[196:199], v[220:223], v[20:23]
	v_mfma_f32_16x16x32_bf16 v[92:95], v[168:171], v[228:231], v[92:95]
	v_mfma_f32_16x16x32_bf16 v[32:35], v[196:199], v[228:231], v[32:35]
	v_mfma_f32_16x16x32_bf16 v[44:47], v[172:175], v[208:211], v[44:47]
	v_mfma_f32_16x16x32_bf16 v[40:43], v[200:203], v[208:211], v[40:43]
	v_mfma_f32_16x16x32_bf16 v[0:3], v[172:175], v[216:219], v[0:3]
	v_mfma_f32_16x16x32_bf16 v[4:7], v[200:203], v[216:219], v[4:7]
	v_mfma_f32_16x16x32_bf16 v[12:15], v[172:175], v[224:227], v[12:15]
	v_mfma_f32_16x16x32_bf16 v[20:23], v[200:203], v[224:227], v[20:23]
	v_mfma_f32_16x16x32_bf16 v[92:95], v[172:175], v[232:235], v[92:95]
	v_mfma_f32_16x16x32_bf16 v[32:35], v[200:203], v[232:235], v[32:35]
	s_barrier
	s_setprio 0
	s_add_i32 s87, 0, 0x18000
	s_add_i32 s88, 0, 0x1c000
	v_add_u32_e32 v158, s87, v167
	v_add_u32_e32 v164, s88, v167
	ds_read_b128 v[128:131], v158
	ds_read_b128 v[132:135], v158 offset:1024
	ds_read_b128 v[136:139], v158 offset:2048
	ds_read_b128 v[158:161], v158 offset:3072
	ds_read_b128 v[168:171], v164
	ds_read_b128 v[172:175], v164 offset:1024
	ds_read_b128 v[196:199], v164 offset:2048
	ds_read_b128 v[200:203], v164 offset:3072
	s_add_u32 s68, s68, 0x40000
	s_addc_u32 s69, s69, 0
	s_mov_b32 m0, s72
	v_lshl_add_u64 v[238:239], s[68:69], 0, v[140:141]
	ds_read_b128 v[204:207], v194 offset:32768
	ds_read_b128 v[208:211], v194 offset:33792
	ds_read_b128 v[212:215], v194 offset:34816
	ds_read_b128 v[216:219], v194 offset:35840
	ds_read_b128 v[220:223], v194 offset:36864
	ds_read_b128 v[224:227], v194 offset:37888
	ds_read_b128 v[228:231], v194 offset:38912
	ds_read_b128 v[232:235], v194 offset:39936
	global_load_lds_dwordx4 v[238:239], off
	v_lshl_add_u64 v[238:239], s[68:69], 0, v[142:143]
	s_mov_b32 m0, s73
	s_nop 0
	global_load_lds_dwordx4 v[238:239], off
	s_waitcnt vmcnt(8)
	s_waitcnt lgkmcnt(0)
	s_setprio 1
	s_barrier
	v_mfma_f32_16x16x32_bf16 v[124:127], v[128:131], v[204:207], v[124:127]
	v_mfma_f32_16x16x32_bf16 v[120:123], v[136:139], v[204:207], v[120:123]
	v_mfma_f32_16x16x32_bf16 v[96:99], v[128:131], v[212:215], v[96:99]
	v_mfma_f32_16x16x32_bf16 v[88:91], v[136:139], v[212:215], v[88:91]
	v_mfma_f32_16x16x32_bf16 v[76:79], v[128:131], v[220:223], v[76:79]
	v_mfma_f32_16x16x32_bf16 v[72:75], v[136:139], v[220:223], v[72:75]
	v_mfma_f32_16x16x32_bf16 v[60:63], v[128:131], v[228:231], v[60:63]
	v_mfma_f32_16x16x32_bf16 v[108:111], v[136:139], v[228:231], v[108:111]
	v_mfma_f32_16x16x32_bf16 v[124:127], v[132:135], v[208:211], v[124:127]
	v_mfma_f32_16x16x32_bf16 v[120:123], v[158:161], v[208:211], v[120:123]
	v_mfma_f32_16x16x32_bf16 v[96:99], v[132:135], v[216:219], v[96:99]
	v_mfma_f32_16x16x32_bf16 v[88:91], v[158:161], v[216:219], v[88:91]
	v_mfma_f32_16x16x32_bf16 v[76:79], v[132:135], v[224:227], v[76:79]
	v_mfma_f32_16x16x32_bf16 v[72:75], v[158:161], v[224:227], v[72:75]
	v_mfma_f32_16x16x32_bf16 v[60:63], v[132:135], v[232:235], v[60:63]
	v_mfma_f32_16x16x32_bf16 v[108:111], v[158:161], v[232:235], v[108:111]
	v_mfma_f32_16x16x32_bf16 v[116:119], v[168:171], v[204:207], v[116:119]
	v_mfma_f32_16x16x32_bf16 v[112:115], v[196:199], v[204:207], v[112:115]
	v_mfma_f32_16x16x32_bf16 v[84:87], v[168:171], v[212:215], v[84:87]
	v_mfma_f32_16x16x32_bf16 v[80:83], v[196:199], v[212:215], v[80:83]
	v_mfma_f32_16x16x32_bf16 v[68:71], v[168:171], v[220:223], v[68:71]
	v_mfma_f32_16x16x32_bf16 v[64:67], v[196:199], v[220:223], v[64:67]
	v_mfma_f32_16x16x32_bf16 v[104:107], v[168:171], v[228:231], v[104:107]
	v_mfma_f32_16x16x32_bf16 v[56:59], v[196:199], v[228:231], v[56:59]
	v_mfma_f32_16x16x32_bf16 v[116:119], v[172:175], v[208:211], v[116:119]
	v_mfma_f32_16x16x32_bf16 v[112:115], v[200:203], v[208:211], v[112:115]
	v_mfma_f32_16x16x32_bf16 v[84:87], v[172:175], v[216:219], v[84:87]
	v_mfma_f32_16x16x32_bf16 v[80:83], v[200:203], v[216:219], v[80:83]
	v_mfma_f32_16x16x32_bf16 v[68:71], v[172:175], v[224:227], v[68:71]
	v_mfma_f32_16x16x32_bf16 v[64:67], v[200:203], v[224:227], v[64:67]
	v_mfma_f32_16x16x32_bf16 v[104:107], v[172:175], v[232:235], v[104:107]
	v_mfma_f32_16x16x32_bf16 v[56:59], v[200:203], v[232:235], v[56:59]
	s_barrier
	s_setprio 0
	s_add_i32 s68, s87, s23
	v_lshl_add_u64 v[162:163], v[162:163], 0, s[36:37]
	s_mov_b32 m0, s68
	ds_read_b128 v[204:207], v194 offset:49152
	ds_read_b128 v[208:211], v194 offset:50176
	ds_read_b128 v[212:215], v194 offset:51200
	ds_read_b128 v[216:219], v194 offset:52224
	ds_read_b128 v[220:223], v194 offset:53248
	ds_read_b128 v[224:227], v194 offset:54272
	ds_read_b128 v[228:231], v194 offset:55296
	ds_read_b128 v[232:235], v194 offset:56320
	global_load_lds_dwordx4 v[162:163], off
	s_add_i32 m0, s68, 0x2000
	s_add_u32 s66, s66, 0x40080
	v_lshl_add_u64 v[162:163], v[178:179], 0, s[36:37]
	s_addc_u32 s67, s67, 0
	s_add_i32 s68, s88, s23
	global_load_lds_dwordx4 v[162:163], off
	v_lshl_add_u64 v[162:163], s[66:67], 0, v[140:141]
	s_mov_b32 m0, s68
	s_nop 0
	global_load_lds_dwordx4 v[162:163], off
	v_lshl_add_u64 v[162:163], s[66:67], 0, v[142:143]
	s_add_i32 m0, s68, 0x2000
	s_nop 0
	global_load_lds_dwordx4 v[162:163], off
	v_lshl_add_u64 v[162:163], v[184:185], 0, s[36:37]
	s_mov_b32 m0, s80
	s_nop 0
	global_load_lds_dwordx4 v[162:163], off
	v_lshl_add_u64 v[162:163], v[236:237], 0, s[36:37]
	s_mov_b32 m0, s81
	s_nop 0
	global_load_lds_dwordx4 v[162:163], off
	s_waitcnt vmcnt(8)
	s_waitcnt lgkmcnt(0)
	s_nop 0
	s_setprio 1
	s_barrier
	v_mfma_f32_16x16x32_bf16 v[52:55], v[128:131], v[204:207], v[52:55]
	v_mfma_f32_16x16x32_bf16 v[48:51], v[136:139], v[204:207], v[48:51]
	v_mfma_f32_16x16x32_bf16 v[16:19], v[128:131], v[212:215], v[16:19]
	v_mfma_f32_16x16x32_bf16 v[8:11], v[136:139], v[212:215], v[8:11]
	v_mfma_f32_16x16x32_bf16 v[28:31], v[128:131], v[220:223], v[28:31]
	v_mfma_f32_16x16x32_bf16 v[24:27], v[136:139], v[220:223], v[24:27]
	v_mfma_f32_16x16x32_bf16 v[36:39], v[128:131], v[228:231], v[36:39]
	v_mfma_f32_16x16x32_bf16 v[100:103], v[136:139], v[228:231], v[100:103]
	v_mfma_f32_16x16x32_bf16 v[52:55], v[132:135], v[208:211], v[52:55]
	v_mfma_f32_16x16x32_bf16 v[48:51], v[158:161], v[208:211], v[48:51]
	v_mfma_f32_16x16x32_bf16 v[16:19], v[132:135], v[216:219], v[16:19]
	v_mfma_f32_16x16x32_bf16 v[8:11], v[158:161], v[216:219], v[8:11]
	v_mfma_f32_16x16x32_bf16 v[28:31], v[132:135], v[224:227], v[28:31]
	v_mfma_f32_16x16x32_bf16 v[24:27], v[158:161], v[224:227], v[24:27]
	v_mfma_f32_16x16x32_bf16 v[36:39], v[132:135], v[232:235], v[36:39]
	v_mfma_f32_16x16x32_bf16 v[100:103], v[158:161], v[232:235], v[100:103]
	v_mfma_f32_16x16x32_bf16 v[44:47], v[168:171], v[204:207], v[44:47]
	v_mfma_f32_16x16x32_bf16 v[40:43], v[196:199], v[204:207], v[40:43]
	v_mfma_f32_16x16x32_bf16 v[0:3], v[168:171], v[212:215], v[0:3]
	v_mfma_f32_16x16x32_bf16 v[4:7], v[196:199], v[212:215], v[4:7]
	v_mfma_f32_16x16x32_bf16 v[12:15], v[168:171], v[220:223], v[12:15]
	v_mfma_f32_16x16x32_bf16 v[20:23], v[196:199], v[220:223], v[20:23]
	v_mfma_f32_16x16x32_bf16 v[92:95], v[168:171], v[228:231], v[92:95]
	v_mfma_f32_16x16x32_bf16 v[32:35], v[196:199], v[228:231], v[32:35]
	v_mfma_f32_16x16x32_bf16 v[44:47], v[172:175], v[208:211], v[44:47]
	v_mfma_f32_16x16x32_bf16 v[40:43], v[200:203], v[208:211], v[40:43]
	v_mfma_f32_16x16x32_bf16 v[0:3], v[172:175], v[216:219], v[0:3]
	v_mfma_f32_16x16x32_bf16 v[4:7], v[200:203], v[216:219], v[4:7]
	v_mfma_f32_16x16x32_bf16 v[12:15], v[172:175], v[224:227], v[12:15]
	v_mfma_f32_16x16x32_bf16 v[20:23], v[200:203], v[224:227], v[20:23]
	v_mfma_f32_16x16x32_bf16 v[92:95], v[172:175], v[232:235], v[92:95]
	v_mfma_f32_16x16x32_bf16 v[32:35], v[200:203], v[232:235], v[32:35]
	s_barrier
	s_setprio 0
	s_add_i32 s86, s86, 2
	s_add_u32 s64, s64, 0x100
	s_addc_u32 s65, s65, 0
	s_add_u32 s84, s84, 0x100
	s_addc_u32 s85, s85, 0
	s_cmp_gt_u32 s86, 13
	s_cbranch_scc0 .LBB0_439
	s_and_b64 vcc, exec, s[38:39]
	s_cbranch_vccz .LBB0_442
	s_barrier

.LBB0_504:
	ds_read_b128 v[104:107], v200
	ds_read_b128 v[108:111], v200 offset:1024
	ds_read_b128 v[124:127], v200 offset:2048
	ds_read_b128 v[128:131], v200 offset:3072
	ds_read_b128 v[144:147], v201
	ds_read_b128 v[148:151], v201 offset:1024
	ds_read_b128 v[152:155], v201 offset:2048
	ds_read_b128 v[156:159], v201 offset:3072
	s_add_u32 s48, s46, 0xfffc0080
	s_addc_u32 s49, s47, -1
	s_cmp_eq_u32 s87, 12
	s_cselect_b32 s51, s39, s49
	s_cselect_b32 s50, s45, s48
	s_cselect_b32 s49, s37, s86
	s_cselect_b32 s48, s84, s85
	v_lshl_add_u64 v[196:197], s[46:47], 0, v[188:189]
	s_add_i32 m0, s52, 0xc000
	ds_read_b128 v[160:163], v202
	ds_read_b128 v[164:167], v202 offset:1024
	ds_read_b128 v[168:171], v202 offset:2048
	ds_read_b128 v[172:175], v202 offset:3072
	ds_read_b128 v[176:179], v202 offset:4096
	ds_read_b128 v[180:183], v202 offset:5120
	ds_read_b128 v[206:209], v202 offset:6144
	ds_read_b128 v[210:213], v202 offset:7168
	global_load_lds_dwordx4 v[196:197], off
	v_lshl_add_u64 v[196:197], s[46:47], 0, v[190:191]
	s_add_i32 m0, s52, 0xe000
	s_nop 0
	global_load_lds_dwordx4 v[196:197], off
	s_waitcnt vmcnt(8)
	s_waitcnt lgkmcnt(0)
	s_setprio 1
	s_barrier
	v_mfma_f32_16x16x32_bf16 v[140:143], v[104:107], v[160:163], v[140:143]
	v_mfma_f32_16x16x32_bf16 v[136:139], v[124:127], v[160:163], v[136:139]
	v_mfma_f32_16x16x32_bf16 v[116:119], v[104:107], v[168:171], v[116:119]
	v_mfma_f32_16x16x32_bf16 v[112:115], v[124:127], v[168:171], v[112:115]
	v_mfma_f32_16x16x32_bf16 v[92:95], v[104:107], v[176:179], v[92:95]
	v_mfma_f32_16x16x32_bf16 v[88:91], v[124:127], v[176:179], v[88:91]
	v_mfma_f32_16x16x32_bf16 v[76:79], v[104:107], v[206:209], v[76:79]
	v_mfma_f32_16x16x32_bf16 v[72:75], v[124:127], v[206:209], v[72:75]
	v_mfma_f32_16x16x32_bf16 v[140:143], v[108:111], v[164:167], v[140:143]
	v_mfma_f32_16x16x32_bf16 v[136:139], v[128:131], v[164:167], v[136:139]
	v_mfma_f32_16x16x32_bf16 v[116:119], v[108:111], v[172:175], v[116:119]
	v_mfma_f32_16x16x32_bf16 v[112:115], v[128:131], v[172:175], v[112:115]
	v_mfma_f32_16x16x32_bf16 v[92:95], v[108:111], v[180:183], v[92:95]
	v_mfma_f32_16x16x32_bf16 v[88:91], v[128:131], v[180:183], v[88:91]
	v_mfma_f32_16x16x32_bf16 v[76:79], v[108:111], v[210:213], v[76:79]
	v_mfma_f32_16x16x32_bf16 v[72:75], v[128:131], v[210:213], v[72:75]
	v_mfma_f32_16x16x32_bf16 v[132:135], v[144:147], v[160:163], v[132:135]
	v_mfma_f32_16x16x32_bf16 v[120:123], v[152:155], v[160:163], v[120:123]
	v_mfma_f32_16x16x32_bf16 v[100:103], v[144:147], v[168:171], v[100:103]
	v_mfma_f32_16x16x32_bf16 v[96:99], v[152:155], v[168:171], v[96:99]
	v_mfma_f32_16x16x32_bf16 v[84:87], v[144:147], v[176:179], v[84:87]
	v_mfma_f32_16x16x32_bf16 v[80:83], v[152:155], v[176:179], v[80:83]
	v_mfma_f32_16x16x32_bf16 v[68:71], v[144:147], v[206:209], v[68:71]
	v_mfma_f32_16x16x32_bf16 v[64:67], v[152:155], v[206:209], v[64:67]
	v_mfma_f32_16x16x32_bf16 v[132:135], v[148:151], v[164:167], v[132:135]
	v_mfma_f32_16x16x32_bf16 v[120:123], v[156:159], v[164:167], v[120:123]
	v_mfma_f32_16x16x32_bf16 v[100:103], v[148:151], v[172:175], v[100:103]
	v_mfma_f32_16x16x32_bf16 v[96:99], v[156:159], v[172:175], v[96:99]
	v_mfma_f32_16x16x32_bf16 v[84:87], v[148:151], v[180:183], v[84:87]
	v_mfma_f32_16x16x32_bf16 v[80:83], v[156:159], v[180:183], v[80:83]
	v_mfma_f32_16x16x32_bf16 v[68:71], v[148:151], v[210:213], v[68:71]
	v_mfma_f32_16x16x32_bf16 v[64:67], v[156:159], v[210:213], v[64:67]
	s_barrier
	s_setprio 0
	s_add_i32 s88, s69, s13
	v_lshl_add_u64 v[196:197], s[48:49], 0, v[184:185]
	s_mov_b32 m0, s88
	ds_read_b128 v[160:163], v202 offset:16384
	ds_read_b128 v[164:167], v202 offset:17408
	ds_read_b128 v[168:171], v202 offset:18432
	ds_read_b128 v[172:175], v202 offset:19456
	ds_read_b128 v[176:179], v202 offset:20480
	ds_read_b128 v[180:183], v202 offset:21504
	ds_read_b128 v[206:209], v202 offset:22528
	ds_read_b128 v[210:213], v202 offset:23552
	global_load_lds_dwordx4 v[196:197], off
	s_add_i32 m0, s88, 0x2000
	s_add_u32 s88, s48, 0x40000
	v_lshl_add_u64 v[214:215], s[48:49], 0, v[186:187]
	s_addc_u32 s89, s49, 0
	s_add_i32 s90, s70, s13
	global_load_lds_dwordx4 v[214:215], off
	v_lshl_add_u64 v[216:217], s[88:89], 0, v[184:185]
	s_mov_b32 m0, s90
	v_lshl_add_u64 v[218:219], s[50:51], 0, v[186:187]
	global_load_lds_dwordx4 v[216:217], off
	v_lshl_add_u64 v[216:217], s[88:89], 0, v[186:187]
	s_add_i32 m0, s90, 0x2000
	s_nop 0
	global_load_lds_dwordx4 v[216:217], off
	v_lshl_add_u64 v[216:217], s[50:51], 0, v[184:185]
	s_mov_b32 m0, s52
	s_nop 0
	global_load_lds_dwordx4 v[216:217], off
	s_mov_b32 m0, s53
	s_nop 0
	global_load_lds_dwordx4 v[218:219], off
	s_waitcnt vmcnt(8)
	s_waitcnt lgkmcnt(0)
	s_setprio 1
	s_barrier
	v_mfma_f32_16x16x32_bf16 v[60:63], v[104:107], v[160:163], v[60:63]
	v_mfma_f32_16x16x32_bf16 v[56:59], v[124:127], v[160:163], v[56:59]
	v_mfma_f32_16x16x32_bf16 v[44:47], v[104:107], v[168:171], v[44:47]
	v_mfma_f32_16x16x32_bf16 v[40:43], v[124:127], v[168:171], v[40:43]
	v_mfma_f32_16x16x32_bf16 v[28:31], v[104:107], v[176:179], v[28:31]
	v_mfma_f32_16x16x32_bf16 v[24:27], v[124:127], v[176:179], v[24:27]
	v_mfma_f32_16x16x32_bf16 v[12:15], v[104:107], v[206:209], v[12:15]
	v_mfma_f32_16x16x32_bf16 v[8:11], v[124:127], v[206:209], v[8:11]
	v_mfma_f32_16x16x32_bf16 v[60:63], v[108:111], v[164:167], v[60:63]
	v_mfma_f32_16x16x32_bf16 v[56:59], v[128:131], v[164:167], v[56:59]
	v_mfma_f32_16x16x32_bf16 v[44:47], v[108:111], v[172:175], v[44:47]
	v_mfma_f32_16x16x32_bf16 v[40:43], v[128:131], v[172:175], v[40:43]
	v_mfma_f32_16x16x32_bf16 v[28:31], v[108:111], v[180:183], v[28:31]
	v_mfma_f32_16x16x32_bf16 v[24:27], v[128:131], v[180:183], v[24:27]
	v_mfma_f32_16x16x32_bf16 v[12:15], v[108:111], v[210:213], v[12:15]
	v_mfma_f32_16x16x32_bf16 v[8:11], v[128:131], v[210:213], v[8:11]
	v_mfma_f32_16x16x32_bf16 v[52:55], v[144:147], v[160:163], v[52:55]
	v_mfma_f32_16x16x32_bf16 v[48:51], v[152:155], v[160:163], v[48:51]
	v_mfma_f32_16x16x32_bf16 v[36:39], v[144:147], v[168:171], v[36:39]
	v_mfma_f32_16x16x32_bf16 v[32:35], v[152:155], v[168:171], v[32:35]
	v_mfma_f32_16x16x32_bf16 v[20:23], v[144:147], v[176:179], v[20:23]
	v_mfma_f32_16x16x32_bf16 v[16:19], v[152:155], v[176:179], v[16:19]
	v_mfma_f32_16x16x32_bf16 v[4:7], v[144:147], v[206:209], v[4:7]
	v_mfma_f32_16x16x32_bf16 v[0:3], v[152:155], v[206:209], v[0:3]
	v_mfma_f32_16x16x32_bf16 v[52:55], v[148:151], v[164:167], v[52:55]
	v_mfma_f32_16x16x32_bf16 v[48:51], v[156:159], v[164:167], v[48:51]
	v_mfma_f32_16x16x32_bf16 v[36:39], v[148:151], v[172:175], v[36:39]
	v_mfma_f32_16x16x32_bf16 v[32:35], v[156:159], v[172:175], v[32:35]
	v_mfma_f32_16x16x32_bf16 v[20:23], v[148:151], v[180:183], v[20:23]
	v_mfma_f32_16x16x32_bf16 v[16:19], v[156:159], v[180:183], v[16:19]
	v_mfma_f32_16x16x32_bf16 v[4:7], v[148:151], v[210:213], v[4:7]
	v_mfma_f32_16x16x32_bf16 v[0:3], v[156:159], v[210:213], v[0:3]
	s_barrier
	s_setprio 0
	s_add_i32 s88, 0, 0x18000
	s_add_i32 s89, 0, 0x1c000
	v_add_u32_e32 v128, s88, v199
	v_add_u32_e32 v156, s89, v199
	ds_read_b128 v[104:107], v128
	ds_read_b128 v[108:111], v128 offset:1024
	ds_read_b128 v[124:127], v128 offset:2048
	ds_read_b128 v[128:131], v128 offset:3072
	ds_read_b128 v[144:147], v156
	ds_read_b128 v[148:151], v156 offset:1024
	ds_read_b128 v[152:155], v156 offset:2048
	ds_read_b128 v[156:159], v156 offset:3072
	s_add_u32 s50, s50, 0x40000
	s_addc_u32 s51, s51, 0
	s_mov_b32 m0, s54
	v_lshl_add_u64 v[220:221], s[50:51], 0, v[184:185]
	ds_read_b128 v[160:163], v202 offset:32768
	ds_read_b128 v[164:167], v202 offset:33792
	ds_read_b128 v[168:171], v202 offset:34816
	ds_read_b128 v[172:175], v202 offset:35840
	ds_read_b128 v[176:179], v202 offset:36864
	ds_read_b128 v[180:183], v202 offset:37888
	ds_read_b128 v[206:209], v202 offset:38912
	ds_read_b128 v[210:213], v202 offset:39936
	global_load_lds_dwordx4 v[220:221], off
	v_lshl_add_u64 v[220:221], s[50:51], 0, v[186:187]
	s_mov_b32 m0, s55
	s_nop 0
	global_load_lds_dwordx4 v[220:221], off
	s_waitcnt vmcnt(8)
	s_waitcnt lgkmcnt(0)
	s_setprio 1
	s_barrier
	v_mfma_f32_16x16x32_bf16 v[140:143], v[104:107], v[160:163], v[140:143]
	v_mfma_f32_16x16x32_bf16 v[136:139], v[124:127], v[160:163], v[136:139]
	v_mfma_f32_16x16x32_bf16 v[116:119], v[104:107], v[168:171], v[116:119]
	v_mfma_f32_16x16x32_bf16 v[112:115], v[124:127], v[168:171], v[112:115]
	v_mfma_f32_16x16x32_bf16 v[92:95], v[104:107], v[176:179], v[92:95]
	v_mfma_f32_16x16x32_bf16 v[88:91], v[124:127], v[176:179], v[88:91]
	v_mfma_f32_16x16x32_bf16 v[76:79], v[104:107], v[206:209], v[76:79]
	v_mfma_f32_16x16x32_bf16 v[72:75], v[124:127], v[206:209], v[72:75]
	v_mfma_f32_16x16x32_bf16 v[140:143], v[108:111], v[164:167], v[140:143]
	v_mfma_f32_16x16x32_bf16 v[136:139], v[128:131], v[164:167], v[136:139]
	v_mfma_f32_16x16x32_bf16 v[116:119], v[108:111], v[172:175], v[116:119]
	v_mfma_f32_16x16x32_bf16 v[112:115], v[128:131], v[172:175], v[112:115]
	v_mfma_f32_16x16x32_bf16 v[92:95], v[108:111], v[180:183], v[92:95]
	v_mfma_f32_16x16x32_bf16 v[88:91], v[128:131], v[180:183], v[88:91]
	v_mfma_f32_16x16x32_bf16 v[76:79], v[108:111], v[210:213], v[76:79]
	v_mfma_f32_16x16x32_bf16 v[72:75], v[128:131], v[210:213], v[72:75]
	v_mfma_f32_16x16x32_bf16 v[132:135], v[144:147], v[160:163], v[132:135]
	v_mfma_f32_16x16x32_bf16 v[120:123], v[152:155], v[160:163], v[120:123]
	v_mfma_f32_16x16x32_bf16 v[100:103], v[144:147], v[168:171], v[100:103]
	v_mfma_f32_16x16x32_bf16 v[96:99], v[152:155], v[168:171], v[96:99]
	v_mfma_f32_16x16x32_bf16 v[84:87], v[144:147], v[176:179], v[84:87]
	v_mfma_f32_16x16x32_bf16 v[80:83], v[152:155], v[176:179], v[80:83]
	v_mfma_f32_16x16x32_bf16 v[68:71], v[144:147], v[206:209], v[68:71]
	v_mfma_f32_16x16x32_bf16 v[64:67], v[152:155], v[206:209], v[64:67]
	v_mfma_f32_16x16x32_bf16 v[132:135], v[148:151], v[164:167], v[132:135]
	v_mfma_f32_16x16x32_bf16 v[120:123], v[156:159], v[164:167], v[120:123]
	v_mfma_f32_16x16x32_bf16 v[100:103], v[148:151], v[172:175], v[100:103]
	v_mfma_f32_16x16x32_bf16 v[96:99], v[156:159], v[172:175], v[96:99]
	v_mfma_f32_16x16x32_bf16 v[84:87], v[148:151], v[180:183], v[84:87]
	v_mfma_f32_16x16x32_bf16 v[80:83], v[156:159], v[180:183], v[80:83]
	v_mfma_f32_16x16x32_bf16 v[68:71], v[148:151], v[210:213], v[68:71]
	v_mfma_f32_16x16x32_bf16 v[64:67], v[156:159], v[210:213], v[64:67]
	s_barrier
	s_setprio 0
	s_add_i32 s50, s88, s13
	v_lshl_add_u64 v[196:197], v[196:197], 0, s[30:31]
	s_mov_b32 m0, s50
	ds_read_b128 v[160:163], v202 offset:49152
	ds_read_b128 v[164:167], v202 offset:50176
	ds_read_b128 v[168:171], v202 offset:51200
	ds_read_b128 v[172:175], v202 offset:52224
	ds_read_b128 v[176:179], v202 offset:53248
	ds_read_b128 v[180:183], v202 offset:54272
	ds_read_b128 v[206:209], v202 offset:55296
	ds_read_b128 v[210:213], v202 offset:56320
	global_load_lds_dwordx4 v[196:197], off
	s_add_i32 m0, s50, 0x2000
	s_add_u32 s48, s48, 0x40080
	v_lshl_add_u64 v[196:197], v[214:215], 0, s[30:31]
	s_addc_u32 s49, s49, 0
	s_add_i32 s50, s89, s13
	global_load_lds_dwordx4 v[196:197], off
	v_lshl_add_u64 v[196:197], s[48:49], 0, v[184:185]
	s_mov_b32 m0, s50
	s_nop 0
	global_load_lds_dwordx4 v[196:197], off
	v_lshl_add_u64 v[196:197], s[48:49], 0, v[186:187]
	s_add_i32 m0, s50, 0x2000
	s_nop 0
	global_load_lds_dwordx4 v[196:197], off
	v_lshl_add_u64 v[196:197], v[216:217], 0, s[30:31]
	s_mov_b32 m0, s61
	s_nop 0
	global_load_lds_dwordx4 v[196:197], off
	v_lshl_add_u64 v[196:197], v[218:219], 0, s[30:31]
	s_mov_b32 m0, s62
	s_nop 0
	global_load_lds_dwordx4 v[196:197], off
	s_waitcnt vmcnt(8)
	s_waitcnt lgkmcnt(0)
	s_nop 0
	s_setprio 1
	s_barrier
	v_mfma_f32_16x16x32_bf16 v[60:63], v[104:107], v[160:163], v[60:63]
	v_mfma_f32_16x16x32_bf16 v[56:59], v[124:127], v[160:163], v[56:59]
	v_mfma_f32_16x16x32_bf16 v[44:47], v[104:107], v[168:171], v[44:47]
	v_mfma_f32_16x16x32_bf16 v[40:43], v[124:127], v[168:171], v[40:43]
	v_mfma_f32_16x16x32_bf16 v[28:31], v[104:107], v[176:179], v[28:31]
	v_mfma_f32_16x16x32_bf16 v[24:27], v[124:127], v[176:179], v[24:27]
	v_mfma_f32_16x16x32_bf16 v[12:15], v[104:107], v[206:209], v[12:15]
	v_mfma_f32_16x16x32_bf16 v[8:11], v[124:127], v[206:209], v[8:11]
	v_mfma_f32_16x16x32_bf16 v[60:63], v[108:111], v[164:167], v[60:63]
	v_mfma_f32_16x16x32_bf16 v[56:59], v[128:131], v[164:167], v[56:59]
	v_mfma_f32_16x16x32_bf16 v[44:47], v[108:111], v[172:175], v[44:47]
	v_mfma_f32_16x16x32_bf16 v[40:43], v[128:131], v[172:175], v[40:43]
	v_mfma_f32_16x16x32_bf16 v[28:31], v[108:111], v[180:183], v[28:31]
	v_mfma_f32_16x16x32_bf16 v[24:27], v[128:131], v[180:183], v[24:27]
	v_mfma_f32_16x16x32_bf16 v[12:15], v[108:111], v[210:213], v[12:15]
	v_mfma_f32_16x16x32_bf16 v[8:11], v[128:131], v[210:213], v[8:11]
	v_mfma_f32_16x16x32_bf16 v[52:55], v[144:147], v[160:163], v[52:55]
	v_mfma_f32_16x16x32_bf16 v[48:51], v[152:155], v[160:163], v[48:51]
	v_mfma_f32_16x16x32_bf16 v[36:39], v[144:147], v[168:171], v[36:39]
	v_mfma_f32_16x16x32_bf16 v[32:35], v[152:155], v[168:171], v[32:35]
	v_mfma_f32_16x16x32_bf16 v[20:23], v[144:147], v[176:179], v[20:23]
	v_mfma_f32_16x16x32_bf16 v[16:19], v[152:155], v[176:179], v[16:19]
	v_mfma_f32_16x16x32_bf16 v[4:7], v[144:147], v[206:209], v[4:7]
	v_mfma_f32_16x16x32_bf16 v[0:3], v[152:155], v[206:209], v[0:3]
	v_mfma_f32_16x16x32_bf16 v[52:55], v[148:151], v[164:167], v[52:55]
	v_mfma_f32_16x16x32_bf16 v[48:51], v[156:159], v[164:167], v[48:51]
	v_mfma_f32_16x16x32_bf16 v[36:39], v[148:151], v[172:175], v[36:39]
	v_mfma_f32_16x16x32_bf16 v[32:35], v[156:159], v[172:175], v[32:35]
	v_mfma_f32_16x16x32_bf16 v[20:23], v[148:151], v[180:183], v[20:23]
	v_mfma_f32_16x16x32_bf16 v[16:19], v[156:159], v[180:183], v[16:19]
	v_mfma_f32_16x16x32_bf16 v[4:7], v[148:151], v[210:213], v[4:7]
	v_mfma_f32_16x16x32_bf16 v[0:3], v[156:159], v[210:213], v[0:3]
	s_barrier
	s_setprio 0
	s_add_i32 s87, s87, 2
	s_add_u32 s46, s46, 0x100
	s_addc_u32 s47, s47, 0
	s_add_u32 s85, s85, 0x100
	s_addc_u32 s86, s86, 0
	s_cmp_gt_u32 s87, 13
	s_cbranch_scc0 .LBB0_504
	s_and_b64 vcc, exec, s[34:35]
	s_cbranch_vccz .LBB0_507
	s_barrier

.LBB0_552:
	ds_read_b128 v[128:131], v173
	ds_read_b128 v[132:135], v173 offset:1024
	ds_read_b128 v[136:139], v173 offset:2048
	ds_read_b128 v[140:143], v173 offset:3072
	ds_read_b128 v[160:163], v179
	ds_read_b128 v[174:177], v179 offset:1024
	ds_read_b128 v[194:197], v179 offset:2048
	ds_read_b128 v[198:201], v179 offset:3072
	s_add_u32 s57, s62, 0xfffc0080
	s_addc_u32 s64, s63, -1
	s_cmp_eq_u32 s55, 12
	s_cselect_b32 s67, s9, s64
	s_cselect_b32 s66, s11, s57
	s_cselect_b32 s65, s13, s23
	s_cselect_b32 s64, s16, s22
	v_lshl_add_u64 v[166:167], s[62:63], 0, v[152:153]
	s_add_i32 m0, s86, 0xc000
	ds_read_b128 v[202:205], v183
	ds_read_b128 v[206:209], v183 offset:1024
	ds_read_b128 v[210:213], v183 offset:2048
	ds_read_b128 v[214:217], v183 offset:3072
	ds_read_b128 v[218:221], v183 offset:4096
	ds_read_b128 v[222:225], v183 offset:5120
	ds_read_b128 v[226:229], v183 offset:6144
	ds_read_b128 v[230:233], v183 offset:7168
	global_load_lds_dwordx4 v[166:167], off
	v_lshl_add_u64 v[166:167], s[62:63], 0, v[154:155]
	s_add_i32 m0, s86, 0xe000
	s_nop 0
	global_load_lds_dwordx4 v[166:167], off
	s_waitcnt vmcnt(8)
	s_waitcnt lgkmcnt(0)
	s_nop 0
	s_setprio 1
	s_barrier
	v_mfma_f32_16x16x32_bf16 v[124:127], v[128:131], v[202:205], v[124:127]
	v_mfma_f32_16x16x32_bf16 v[120:123], v[136:139], v[202:205], v[120:123]
	v_mfma_f32_16x16x32_bf16 v[108:111], v[128:131], v[210:213], v[108:111]
	v_mfma_f32_16x16x32_bf16 v[104:107], v[136:139], v[210:213], v[104:107]
	v_mfma_f32_16x16x32_bf16 v[92:95], v[128:131], v[218:221], v[92:95]
	v_mfma_f32_16x16x32_bf16 v[88:91], v[136:139], v[218:221], v[88:91]
	v_mfma_f32_16x16x32_bf16 v[76:79], v[128:131], v[226:229], v[76:79]
	v_mfma_f32_16x16x32_bf16 v[72:75], v[136:139], v[226:229], v[72:75]
	v_mfma_f32_16x16x32_bf16 v[124:127], v[132:135], v[206:209], v[124:127]
	v_mfma_f32_16x16x32_bf16 v[120:123], v[140:143], v[206:209], v[120:123]
	v_mfma_f32_16x16x32_bf16 v[108:111], v[132:135], v[214:217], v[108:111]
	v_mfma_f32_16x16x32_bf16 v[104:107], v[140:143], v[214:217], v[104:107]
	v_mfma_f32_16x16x32_bf16 v[92:95], v[132:135], v[222:225], v[92:95]
	v_mfma_f32_16x16x32_bf16 v[88:91], v[140:143], v[222:225], v[88:91]
	v_mfma_f32_16x16x32_bf16 v[76:79], v[132:135], v[230:233], v[76:79]
	v_mfma_f32_16x16x32_bf16 v[72:75], v[140:143], v[230:233], v[72:75]
	v_mfma_f32_16x16x32_bf16 v[116:119], v[160:163], v[202:205], v[116:119]
	v_mfma_f32_16x16x32_bf16 v[112:115], v[194:197], v[202:205], v[112:115]
	v_mfma_f32_16x16x32_bf16 v[100:103], v[160:163], v[210:213], v[100:103]
	v_mfma_f32_16x16x32_bf16 v[96:99], v[194:197], v[210:213], v[96:99]
	v_mfma_f32_16x16x32_bf16 v[84:87], v[160:163], v[218:221], v[84:87]
	v_mfma_f32_16x16x32_bf16 v[80:83], v[194:197], v[218:221], v[80:83]
	v_mfma_f32_16x16x32_bf16 v[68:71], v[160:163], v[226:229], v[68:71]
	v_mfma_f32_16x16x32_bf16 v[64:67], v[194:197], v[226:229], v[64:67]
	v_mfma_f32_16x16x32_bf16 v[116:119], v[174:177], v[206:209], v[116:119]
	v_mfma_f32_16x16x32_bf16 v[112:115], v[198:201], v[206:209], v[112:115]
	v_mfma_f32_16x16x32_bf16 v[100:103], v[174:177], v[214:217], v[100:103]
	v_mfma_f32_16x16x32_bf16 v[96:99], v[198:201], v[214:217], v[96:99]
	v_mfma_f32_16x16x32_bf16 v[84:87], v[174:177], v[222:225], v[84:87]
	v_mfma_f32_16x16x32_bf16 v[80:83], v[198:201], v[222:225], v[80:83]
	v_mfma_f32_16x16x32_bf16 v[68:71], v[174:177], v[230:233], v[68:71]
	v_mfma_f32_16x16x32_bf16 v[64:67], v[198:201], v[230:233], v[64:67]
	s_barrier
	s_setprio 0
	s_add_i32 s57, s0, s85
	v_lshl_add_u64 v[166:167], s[64:65], 0, v[144:145]
	s_mov_b32 m0, s57
	ds_read_b128 v[202:205], v183 offset:16384
	ds_read_b128 v[206:209], v183 offset:17408
	ds_read_b128 v[210:213], v183 offset:18432
	ds_read_b128 v[214:217], v183 offset:19456
	ds_read_b128 v[218:221], v183 offset:20480
	ds_read_b128 v[222:225], v183 offset:21504
	ds_read_b128 v[226:229], v183 offset:22528
	ds_read_b128 v[230:233], v183 offset:23552
	global_load_lds_dwordx4 v[166:167], off
	s_add_i32 m0, s57, 0x2000
	s_add_u32 s68, s64, 0x40000
	v_lshl_add_u64 v[170:171], s[64:65], 0, v[146:147]
	s_addc_u32 s69, s65, 0
	s_add_i32 s57, s1, s85
	global_load_lds_dwordx4 v[170:171], off
	v_lshl_add_u64 v[180:181], s[68:69], 0, v[144:145]
	s_mov_b32 m0, s57
	v_lshl_add_u64 v[184:185], s[66:67], 0, v[146:147]
	global_load_lds_dwordx4 v[180:181], off
	v_lshl_add_u64 v[180:181], s[68:69], 0, v[146:147]
	s_add_i32 m0, s57, 0x2000
	s_nop 0
	global_load_lds_dwordx4 v[180:181], off
	v_lshl_add_u64 v[180:181], s[66:67], 0, v[144:145]
	s_mov_b32 m0, s86
	s_nop 0
	global_load_lds_dwordx4 v[180:181], off
	s_mov_b32 m0, s87
	s_nop 0
	global_load_lds_dwordx4 v[184:185], off
	s_waitcnt vmcnt(8)
	s_waitcnt lgkmcnt(0)
	s_setprio 1
	s_barrier
	v_mfma_f32_16x16x32_bf16 v[60:63], v[128:131], v[202:205], v[60:63]
	v_mfma_f32_16x16x32_bf16 v[56:59], v[136:139], v[202:205], v[56:59]
	v_mfma_f32_16x16x32_bf16 v[44:47], v[128:131], v[210:213], v[44:47]
	v_mfma_f32_16x16x32_bf16 v[40:43], v[136:139], v[210:213], v[40:43]
	v_mfma_f32_16x16x32_bf16 v[28:31], v[128:131], v[218:221], v[28:31]
	v_mfma_f32_16x16x32_bf16 v[24:27], v[136:139], v[218:221], v[24:27]
	v_mfma_f32_16x16x32_bf16 v[12:15], v[128:131], v[226:229], v[12:15]
	v_mfma_f32_16x16x32_bf16 v[8:11], v[136:139], v[226:229], v[8:11]
	v_mfma_f32_16x16x32_bf16 v[60:63], v[132:135], v[206:209], v[60:63]
	v_mfma_f32_16x16x32_bf16 v[56:59], v[140:143], v[206:209], v[56:59]
	v_mfma_f32_16x16x32_bf16 v[44:47], v[132:135], v[214:217], v[44:47]
	v_mfma_f32_16x16x32_bf16 v[40:43], v[140:143], v[214:217], v[40:43]
	v_mfma_f32_16x16x32_bf16 v[28:31], v[132:135], v[222:225], v[28:31]
	v_mfma_f32_16x16x32_bf16 v[24:27], v[140:143], v[222:225], v[24:27]
	v_mfma_f32_16x16x32_bf16 v[12:15], v[132:135], v[230:233], v[12:15]
	v_mfma_f32_16x16x32_bf16 v[8:11], v[140:143], v[230:233], v[8:11]
	v_mfma_f32_16x16x32_bf16 v[52:55], v[160:163], v[202:205], v[52:55]
	v_mfma_f32_16x16x32_bf16 v[48:51], v[194:197], v[202:205], v[48:51]
	v_mfma_f32_16x16x32_bf16 v[36:39], v[160:163], v[210:213], v[36:39]
	v_mfma_f32_16x16x32_bf16 v[32:35], v[194:197], v[210:213], v[32:35]
	v_mfma_f32_16x16x32_bf16 v[20:23], v[160:163], v[218:221], v[20:23]
	v_mfma_f32_16x16x32_bf16 v[16:19], v[194:197], v[218:221], v[16:19]
	v_mfma_f32_16x16x32_bf16 v[4:7], v[160:163], v[226:229], v[4:7]
	v_mfma_f32_16x16x32_bf16 v[0:3], v[194:197], v[226:229], v[0:3]
	v_mfma_f32_16x16x32_bf16 v[52:55], v[174:177], v[206:209], v[52:55]
	v_mfma_f32_16x16x32_bf16 v[48:51], v[198:201], v[206:209], v[48:51]
	v_mfma_f32_16x16x32_bf16 v[36:39], v[174:177], v[214:217], v[36:39]
	v_mfma_f32_16x16x32_bf16 v[32:35], v[198:201], v[214:217], v[32:35]
	v_mfma_f32_16x16x32_bf16 v[20:23], v[174:177], v[222:225], v[20:23]
	v_mfma_f32_16x16x32_bf16 v[16:19], v[198:201], v[222:225], v[16:19]
	v_mfma_f32_16x16x32_bf16 v[4:7], v[174:177], v[230:233], v[4:7]
	v_mfma_f32_16x16x32_bf16 v[0:3], v[198:201], v[230:233], v[0:3]
	s_barrier
	s_setprio 0
	s_add_i32 s57, 0, 0x18000
	s_add_i32 s68, 0, 0x1c000
	v_add_u32_e32 v140, s57, v169
	v_add_u32_e32 v148, s68, v169
	ds_read_b128 v[128:131], v140
	ds_read_b128 v[132:135], v140 offset:1024
	ds_read_b128 v[136:139], v140 offset:2048
	ds_read_b128 v[140:143], v140 offset:3072
	ds_read_b128 v[160:163], v148
	ds_read_b128 v[174:177], v148 offset:1024
	ds_read_b128 v[194:197], v148 offset:2048
	ds_read_b128 v[198:201], v148 offset:3072
	s_add_u32 s66, s66, 0x40000
	s_addc_u32 s67, s67, 0
	s_mov_b32 m0, s88
	v_lshl_add_u64 v[188:189], s[66:67], 0, v[144:145]
	ds_read_b128 v[202:205], v183 offset:32768
	ds_read_b128 v[206:209], v183 offset:33792
	ds_read_b128 v[210:213], v183 offset:34816
	ds_read_b128 v[214:217], v183 offset:35840
	ds_read_b128 v[218:221], v183 offset:36864
	ds_read_b128 v[222:225], v183 offset:37888
	ds_read_b128 v[226:229], v183 offset:38912
	ds_read_b128 v[230:233], v183 offset:39936
	global_load_lds_dwordx4 v[188:189], off
	v_lshl_add_u64 v[188:189], s[66:67], 0, v[146:147]
	s_mov_b32 m0, s89
	s_nop 0
	global_load_lds_dwordx4 v[188:189], off
	s_waitcnt vmcnt(8)
	s_waitcnt lgkmcnt(0)
	s_setprio 1
	s_barrier
	v_mfma_f32_16x16x32_bf16 v[124:127], v[128:131], v[202:205], v[124:127]
	v_mfma_f32_16x16x32_bf16 v[120:123], v[136:139], v[202:205], v[120:123]
	v_mfma_f32_16x16x32_bf16 v[108:111], v[128:131], v[210:213], v[108:111]
	v_mfma_f32_16x16x32_bf16 v[104:107], v[136:139], v[210:213], v[104:107]
	v_mfma_f32_16x16x32_bf16 v[92:95], v[128:131], v[218:221], v[92:95]
	v_mfma_f32_16x16x32_bf16 v[88:91], v[136:139], v[218:221], v[88:91]
	v_mfma_f32_16x16x32_bf16 v[76:79], v[128:131], v[226:229], v[76:79]
	v_mfma_f32_16x16x32_bf16 v[72:75], v[136:139], v[226:229], v[72:75]
	v_mfma_f32_16x16x32_bf16 v[124:127], v[132:135], v[206:209], v[124:127]
	v_mfma_f32_16x16x32_bf16 v[120:123], v[140:143], v[206:209], v[120:123]
	v_mfma_f32_16x16x32_bf16 v[108:111], v[132:135], v[214:217], v[108:111]
	v_mfma_f32_16x16x32_bf16 v[104:107], v[140:143], v[214:217], v[104:107]
	v_mfma_f32_16x16x32_bf16 v[92:95], v[132:135], v[222:225], v[92:95]
	v_mfma_f32_16x16x32_bf16 v[88:91], v[140:143], v[222:225], v[88:91]
	v_mfma_f32_16x16x32_bf16 v[76:79], v[132:135], v[230:233], v[76:79]
	v_mfma_f32_16x16x32_bf16 v[72:75], v[140:143], v[230:233], v[72:75]
	v_mfma_f32_16x16x32_bf16 v[116:119], v[160:163], v[202:205], v[116:119]
	v_mfma_f32_16x16x32_bf16 v[112:115], v[194:197], v[202:205], v[112:115]
	v_mfma_f32_16x16x32_bf16 v[100:103], v[160:163], v[210:213], v[100:103]
	v_mfma_f32_16x16x32_bf16 v[96:99], v[194:197], v[210:213], v[96:99]
	v_mfma_f32_16x16x32_bf16 v[84:87], v[160:163], v[218:221], v[84:87]
	v_mfma_f32_16x16x32_bf16 v[80:83], v[194:197], v[218:221], v[80:83]
	v_mfma_f32_16x16x32_bf16 v[68:71], v[160:163], v[226:229], v[68:71]
	v_mfma_f32_16x16x32_bf16 v[64:67], v[194:197], v[226:229], v[64:67]
	v_mfma_f32_16x16x32_bf16 v[116:119], v[174:177], v[206:209], v[116:119]
	v_mfma_f32_16x16x32_bf16 v[112:115], v[198:201], v[206:209], v[112:115]
	v_mfma_f32_16x16x32_bf16 v[100:103], v[174:177], v[214:217], v[100:103]
	v_mfma_f32_16x16x32_bf16 v[96:99], v[198:201], v[214:217], v[96:99]
	v_mfma_f32_16x16x32_bf16 v[84:87], v[174:177], v[222:225], v[84:87]
	v_mfma_f32_16x16x32_bf16 v[80:83], v[198:201], v[222:225], v[80:83]
	v_mfma_f32_16x16x32_bf16 v[68:71], v[174:177], v[230:233], v[68:71]
	v_mfma_f32_16x16x32_bf16 v[64:67], v[198:201], v[230:233], v[64:67]
	s_barrier
	s_setprio 0
	s_add_i32 s57, s57, s85
	v_lshl_add_u64 v[166:167], v[166:167], 0, s[42:43]
	s_mov_b32 m0, s57
	ds_read_b128 v[202:205], v183 offset:49152
	ds_read_b128 v[206:209], v183 offset:50176
	ds_read_b128 v[210:213], v183 offset:51200
	ds_read_b128 v[214:217], v183 offset:52224
	ds_read_b128 v[218:221], v183 offset:53248
	ds_read_b128 v[222:225], v183 offset:54272
	ds_read_b128 v[226:229], v183 offset:55296
	ds_read_b128 v[230:233], v183 offset:56320
	global_load_lds_dwordx4 v[166:167], off
	s_add_i32 m0, s57, 0x2000
	s_add_u32 s64, s64, 0x40080
	v_lshl_add_u64 v[166:167], v[170:171], 0, s[42:43]
	s_addc_u32 s65, s65, 0
	s_add_i32 s57, s68, s85
	global_load_lds_dwordx4 v[166:167], off
	v_lshl_add_u64 v[166:167], s[64:65], 0, v[144:145]
	s_mov_b32 m0, s57
	s_nop 0
	global_load_lds_dwordx4 v[166:167], off
	v_lshl_add_u64 v[166:167], s[64:65], 0, v[146:147]
	s_add_i32 m0, s57, 0x2000
	s_nop 0
	global_load_lds_dwordx4 v[166:167], off
	v_lshl_add_u64 v[166:167], v[180:181], 0, s[42:43]
	s_mov_b32 m0, s94
	s_nop 0
	global_load_lds_dwordx4 v[166:167], off
	v_lshl_add_u64 v[166:167], v[184:185], 0, s[42:43]
	s_mov_b32 m0, s95
	s_nop 0
	global_load_lds_dwordx4 v[166:167], off
	s_waitcnt vmcnt(8)
	s_waitcnt lgkmcnt(0)
	s_nop 0
	s_setprio 1
	s_barrier
	v_mfma_f32_16x16x32_bf16 v[60:63], v[128:131], v[202:205], v[60:63]
	v_mfma_f32_16x16x32_bf16 v[56:59], v[136:139], v[202:205], v[56:59]
	v_mfma_f32_16x16x32_bf16 v[44:47], v[128:131], v[210:213], v[44:47]
	v_mfma_f32_16x16x32_bf16 v[40:43], v[136:139], v[210:213], v[40:43]
	v_mfma_f32_16x16x32_bf16 v[28:31], v[128:131], v[218:221], v[28:31]
	v_mfma_f32_16x16x32_bf16 v[24:27], v[136:139], v[218:221], v[24:27]
	v_mfma_f32_16x16x32_bf16 v[12:15], v[128:131], v[226:229], v[12:15]
	v_mfma_f32_16x16x32_bf16 v[8:11], v[136:139], v[226:229], v[8:11]
	v_mfma_f32_16x16x32_bf16 v[60:63], v[132:135], v[206:209], v[60:63]
	v_mfma_f32_16x16x32_bf16 v[56:59], v[140:143], v[206:209], v[56:59]
	v_mfma_f32_16x16x32_bf16 v[44:47], v[132:135], v[214:217], v[44:47]
	v_mfma_f32_16x16x32_bf16 v[40:43], v[140:143], v[214:217], v[40:43]
	v_mfma_f32_16x16x32_bf16 v[28:31], v[132:135], v[222:225], v[28:31]
	v_mfma_f32_16x16x32_bf16 v[24:27], v[140:143], v[222:225], v[24:27]
	v_mfma_f32_16x16x32_bf16 v[12:15], v[132:135], v[230:233], v[12:15]
	v_mfma_f32_16x16x32_bf16 v[8:11], v[140:143], v[230:233], v[8:11]
	v_mfma_f32_16x16x32_bf16 v[52:55], v[160:163], v[202:205], v[52:55]
	v_mfma_f32_16x16x32_bf16 v[48:51], v[194:197], v[202:205], v[48:51]
	v_mfma_f32_16x16x32_bf16 v[36:39], v[160:163], v[210:213], v[36:39]
	v_mfma_f32_16x16x32_bf16 v[32:35], v[194:197], v[210:213], v[32:35]
	v_mfma_f32_16x16x32_bf16 v[20:23], v[160:163], v[218:221], v[20:23]
	v_mfma_f32_16x16x32_bf16 v[16:19], v[194:197], v[218:221], v[16:19]
	v_mfma_f32_16x16x32_bf16 v[4:7], v[160:163], v[226:229], v[4:7]
	v_mfma_f32_16x16x32_bf16 v[0:3], v[194:197], v[226:229], v[0:3]
	v_mfma_f32_16x16x32_bf16 v[52:55], v[174:177], v[206:209], v[52:55]
	v_mfma_f32_16x16x32_bf16 v[48:51], v[198:201], v[206:209], v[48:51]
	v_mfma_f32_16x16x32_bf16 v[36:39], v[174:177], v[214:217], v[36:39]
	v_mfma_f32_16x16x32_bf16 v[32:35], v[198:201], v[214:217], v[32:35]
	v_mfma_f32_16x16x32_bf16 v[20:23], v[174:177], v[222:225], v[20:23]
	v_mfma_f32_16x16x32_bf16 v[16:19], v[198:201], v[222:225], v[16:19]
	v_mfma_f32_16x16x32_bf16 v[4:7], v[174:177], v[230:233], v[4:7]
	v_mfma_f32_16x16x32_bf16 v[0:3], v[198:201], v[230:233], v[0:3]
	s_barrier
	s_setprio 0
	s_add_i32 s55, s55, 2
	s_add_u32 s62, s62, 0x100
	s_addc_u32 s63, s63, 0
	s_add_u32 s22, s22, 0x100
	s_addc_u32 s23, s23, 0
	s_cmp_gt_u32 s55, 13
	s_cbranch_scc0 .LBB0_552
	s_and_b64 vcc, exec, s[44:45]
	s_cbranch_vccz .LBB0_555
	s_barrier

.LBB0_744:
	s_add_u32 s54, s42, s48
	s_addc_u32 s55, s43, s49
	s_add_u32 s52, s54, 0x100
	s_addc_u32 s53, s55, 0
	s_and_b64 s[50:51], s[46:47], exec
	s_cselect_b32 s51, s35, s53
	s_cselect_b32 s50, s82, s52
	s_add_u32 s48, s40, s48
	s_addc_u32 s49, s41, s49
	s_add_u32 s48, s48, 0x100
	s_addc_u32 s49, s49, 0
	s_and_b64 s[46:47], s[46:47], exec
	s_cselect_b32 s53, s31, s49
	s_cselect_b32 s52, s83, s48
	s_cselect_b32 s98, 1, 0
	s_add_u32 s56, s54, 0x10080
	ds_read_b128 v[150:153], v144
	ds_read_b128 v[154:157], v144 offset:1024
	ds_read_b128 v[158:161], v144 offset:2048
	ds_read_b128 v[162:165], v144 offset:3072
	ds_read_b128 v[166:169], v145
	ds_read_b128 v[170:173], v145 offset:1024
	ds_read_b128 v[174:177], v145 offset:2048
	ds_read_b128 v[178:181], v145 offset:3072
	s_addc_u32 s57, s55, 0
	s_add_i32 s93, s74, s60
	s_add_i32 m0, s61, 0xc000
	s_add_i32 s94, s61, 0xe000
	s_add_i32 s90, s93, 0x2000
	s_add_u32 s54, s52, 0x10000
	s_addc_u32 s55, s53, 0
	s_add_i32 s92, s75, s60
	s_add_i32 s91, s92, 0x2000
	s_add_i32 s89, 0, 0x18000
	s_add_i32 s88, 0, 0x1c000
	s_add_u32 s48, s50, 0x10000
	s_addc_u32 s49, s51, 0
	s_add_i32 s87, s89, s60
	s_add_i32 s85, s87, 0x2000
	s_add_u32 s46, s52, 0x10080
	s_addc_u32 s47, s53, 0
	s_add_i32 s86, s88, s60
	s_add_i32 s84, s86, 0x2000
	v_lshl_add_u64 v[138:139], s[56:57], 0, v[130:131]
	ds_read_b128 v[182:185], v146
	ds_read_b128 v[186:189], v146 offset:1024
	ds_read_b128 v[190:193], v146 offset:2048
	ds_read_b128 v[194:197], v146 offset:3072
	ds_read_b128 v[198:201], v146 offset:4096
	ds_read_b128 v[202:205], v146 offset:5120
	ds_read_b128 v[206:209], v146 offset:6144
	ds_read_b128 v[210:213], v146 offset:7168
	global_load_lds_dwordx4 v[138:139], off
	v_lshl_add_u64 v[138:139], s[56:57], 0, v[128:129]
	s_mov_b32 m0, s94
	s_nop 0
	global_load_lds_dwordx4 v[138:139], off
	s_waitcnt vmcnt(8)
	s_waitcnt lgkmcnt(0)
	s_nop 0
	s_setprio 1
	s_cmp_lg_u32 s98, 0
	s_cbranch_scc0 .Lkv_nopf
	v_lshl_add_u32 v138, s18, 8, v141
	v_ashrrev_i32_e32 v139, 31, v138
	v_lshl_add_u64 v[138:139], v[138:139], 4, s[14:15]
	global_load_dwordx4 v[222:225], v[138:139], off
	global_load_dwordx4 v[226:229], v[138:139], off offset:256
	global_load_dwordx4 v[230:233], v[138:139], off offset:512
	global_load_dwordx4 v[234:237], v[138:139], off offset:768
	global_load_dwordx4 v[238:241], v[138:139], off offset:2048
	global_load_dwordx4 v[242:245], v[138:139], off offset:2304
	global_load_dwordx4 v[248:251], v[138:139], off offset:2560
	global_load_dwordx4 v[252:255], v[138:139], off offset:2816
.Lkv_nopf:
	s_barrier
	v_mfma_f32_16x16x32_bf16 v[124:127], v[150:153], v[182:185], v[124:127]
	v_mfma_f32_16x16x32_bf16 v[120:123], v[158:161], v[182:185], v[120:123]
	v_mfma_f32_16x16x32_bf16 v[108:111], v[150:153], v[190:193], v[108:111]
	v_mfma_f32_16x16x32_bf16 v[104:107], v[158:161], v[190:193], v[104:107]
	v_mfma_f32_16x16x32_bf16 v[92:95], v[150:153], v[198:201], v[92:95]
	v_mfma_f32_16x16x32_bf16 v[88:91], v[158:161], v[198:201], v[88:91]
	v_mfma_f32_16x16x32_bf16 v[76:79], v[150:153], v[206:209], v[76:79]
	v_mfma_f32_16x16x32_bf16 v[72:75], v[158:161], v[206:209], v[72:75]
	v_mfma_f32_16x16x32_bf16 v[124:127], v[154:157], v[186:189], v[124:127]
	v_mfma_f32_16x16x32_bf16 v[120:123], v[162:165], v[186:189], v[120:123]
	v_mfma_f32_16x16x32_bf16 v[108:111], v[154:157], v[194:197], v[108:111]
	v_mfma_f32_16x16x32_bf16 v[104:107], v[162:165], v[194:197], v[104:107]
	v_mfma_f32_16x16x32_bf16 v[92:95], v[154:157], v[202:205], v[92:95]
	v_mfma_f32_16x16x32_bf16 v[88:91], v[162:165], v[202:205], v[88:91]
	v_mfma_f32_16x16x32_bf16 v[76:79], v[154:157], v[210:213], v[76:79]
	v_mfma_f32_16x16x32_bf16 v[72:75], v[162:165], v[210:213], v[72:75]
	v_mfma_f32_16x16x32_bf16 v[116:119], v[166:169], v[182:185], v[116:119]
	v_mfma_f32_16x16x32_bf16 v[112:115], v[174:177], v[182:185], v[112:115]
	v_mfma_f32_16x16x32_bf16 v[100:103], v[166:169], v[190:193], v[100:103]
	v_mfma_f32_16x16x32_bf16 v[96:99], v[174:177], v[190:193], v[96:99]
	v_mfma_f32_16x16x32_bf16 v[84:87], v[166:169], v[198:201], v[84:87]
	v_mfma_f32_16x16x32_bf16 v[80:83], v[174:177], v[198:201], v[80:83]
	v_mfma_f32_16x16x32_bf16 v[68:71], v[166:169], v[206:209], v[68:71]
	v_mfma_f32_16x16x32_bf16 v[64:67], v[174:177], v[206:209], v[64:67]
	v_mfma_f32_16x16x32_bf16 v[116:119], v[170:173], v[186:189], v[116:119]
	v_mfma_f32_16x16x32_bf16 v[112:115], v[178:181], v[186:189], v[112:115]
	v_mfma_f32_16x16x32_bf16 v[100:103], v[170:173], v[194:197], v[100:103]
	v_mfma_f32_16x16x32_bf16 v[96:99], v[178:181], v[194:197], v[96:99]
	v_mfma_f32_16x16x32_bf16 v[84:87], v[170:173], v[202:205], v[84:87]
	v_mfma_f32_16x16x32_bf16 v[80:83], v[178:181], v[202:205], v[80:83]
	v_mfma_f32_16x16x32_bf16 v[68:71], v[170:173], v[210:213], v[68:71]
	v_mfma_f32_16x16x32_bf16 v[64:67], v[178:181], v[210:213], v[64:67]
	s_barrier
	s_setprio 0
	s_mov_b32 m0, s93
	v_lshl_add_u64 v[138:139], s[52:53], 0, v[130:131]
	ds_read_b128 v[182:185], v146 offset:16384
	ds_read_b128 v[186:189], v146 offset:17408
	ds_read_b128 v[190:193], v146 offset:18432
	ds_read_b128 v[194:197], v146 offset:19456
	ds_read_b128 v[198:201], v146 offset:20480
	ds_read_b128 v[202:205], v146 offset:21504
	ds_read_b128 v[206:209], v146 offset:22528
	ds_read_b128 v[210:213], v146 offset:23552
	global_load_lds_dwordx4 v[138:139], off
	v_lshl_add_u64 v[214:215], s[52:53], 0, v[128:129]
	s_mov_b32 m0, s90
	v_lshl_add_u64 v[216:217], s[54:55], 0, v[130:131]
	global_load_lds_dwordx4 v[214:215], off
	s_mov_b32 m0, s92
	v_lshl_add_u64 v[218:219], s[50:51], 0, v[128:129]
	global_load_lds_dwordx4 v[216:217], off
	v_lshl_add_u64 v[216:217], s[54:55], 0, v[128:129]
	s_mov_b32 m0, s91
	s_nop 0
	global_load_lds_dwordx4 v[216:217], off
	v_lshl_add_u64 v[216:217], s[50:51], 0, v[130:131]
	s_mov_b32 m0, s61
	s_nop 0
	global_load_lds_dwordx4 v[216:217], off
	s_mov_b32 m0, s62
	s_nop 0
	global_load_lds_dwordx4 v[218:219], off
	s_waitcnt vmcnt(8)
	s_waitcnt lgkmcnt(0)
	s_nop 0
	s_setprio 1
	s_barrier
	v_mfma_f32_16x16x32_bf16 v[60:63], v[150:153], v[182:185], v[60:63]
	v_mfma_f32_16x16x32_bf16 v[56:59], v[158:161], v[182:185], v[56:59]
	v_mfma_f32_16x16x32_bf16 v[44:47], v[150:153], v[190:193], v[44:47]
	v_mfma_f32_16x16x32_bf16 v[40:43], v[158:161], v[190:193], v[40:43]
	v_mfma_f32_16x16x32_bf16 v[28:31], v[150:153], v[198:201], v[28:31]
	v_mfma_f32_16x16x32_bf16 v[24:27], v[158:161], v[198:201], v[24:27]
	v_mfma_f32_16x16x32_bf16 v[12:15], v[150:153], v[206:209], v[12:15]
	v_mfma_f32_16x16x32_bf16 v[8:11], v[158:161], v[206:209], v[8:11]
	v_mfma_f32_16x16x32_bf16 v[60:63], v[154:157], v[186:189], v[60:63]
	v_mfma_f32_16x16x32_bf16 v[56:59], v[162:165], v[186:189], v[56:59]
	v_mfma_f32_16x16x32_bf16 v[44:47], v[154:157], v[194:197], v[44:47]
	v_mfma_f32_16x16x32_bf16 v[40:43], v[162:165], v[194:197], v[40:43]
	v_mfma_f32_16x16x32_bf16 v[28:31], v[154:157], v[202:205], v[28:31]
	v_mfma_f32_16x16x32_bf16 v[24:27], v[162:165], v[202:205], v[24:27]
	v_mfma_f32_16x16x32_bf16 v[12:15], v[154:157], v[210:213], v[12:15]
	v_mfma_f32_16x16x32_bf16 v[8:11], v[162:165], v[210:213], v[8:11]
	v_mfma_f32_16x16x32_bf16 v[52:55], v[166:169], v[182:185], v[52:55]
	v_mfma_f32_16x16x32_bf16 v[48:51], v[174:177], v[182:185], v[48:51]
	v_mfma_f32_16x16x32_bf16 v[36:39], v[166:169], v[190:193], v[36:39]
	v_mfma_f32_16x16x32_bf16 v[32:35], v[174:177], v[190:193], v[32:35]
	v_mfma_f32_16x16x32_bf16 v[20:23], v[166:169], v[198:201], v[20:23]
	v_mfma_f32_16x16x32_bf16 v[16:19], v[174:177], v[198:201], v[16:19]
	v_mfma_f32_16x16x32_bf16 v[4:7], v[166:169], v[206:209], v[4:7]
	v_mfma_f32_16x16x32_bf16 v[0:3], v[174:177], v[206:209], v[0:3]
	v_mfma_f32_16x16x32_bf16 v[52:55], v[170:173], v[186:189], v[52:55]
	v_mfma_f32_16x16x32_bf16 v[48:51], v[178:181], v[186:189], v[48:51]
	v_mfma_f32_16x16x32_bf16 v[36:39], v[170:173], v[194:197], v[36:39]
	v_mfma_f32_16x16x32_bf16 v[32:35], v[178:181], v[194:197], v[32:35]
	v_mfma_f32_16x16x32_bf16 v[20:23], v[170:173], v[202:205], v[20:23]
	v_mfma_f32_16x16x32_bf16 v[16:19], v[178:181], v[202:205], v[16:19]
	v_mfma_f32_16x16x32_bf16 v[4:7], v[170:173], v[210:213], v[4:7]
	v_mfma_f32_16x16x32_bf16 v[0:3], v[178:181], v[210:213], v[0:3]
	s_barrier
	s_setprio 0
	v_add_u32_e32 v132, s89, v143
	ds_read_b128 v[150:153], v132
	ds_read_b128 v[154:157], v132 offset:1024
	ds_read_b128 v[158:161], v132 offset:2048
	ds_read_b128 v[162:165], v132 offset:3072
	v_add_u32_e32 v132, s88, v143
	ds_read_b128 v[166:169], v132
	ds_read_b128 v[170:173], v132 offset:1024
	ds_read_b128 v[174:177], v132 offset:2048
	ds_read_b128 v[178:181], v132 offset:3072
	s_mov_b32 m0, s63
	v_lshl_add_u64 v[220:221], s[48:49], 0, v[130:131]
	ds_read_b128 v[182:185], v146 offset:32768
	ds_read_b128 v[186:189], v146 offset:33792
	ds_read_b128 v[190:193], v146 offset:34816
	ds_read_b128 v[194:197], v146 offset:35840
	ds_read_b128 v[198:201], v146 offset:36864
	ds_read_b128 v[202:205], v146 offset:37888
	ds_read_b128 v[206:209], v146 offset:38912
	ds_read_b128 v[210:213], v146 offset:39936
	global_load_lds_dwordx4 v[220:221], off
	v_lshl_add_u64 v[220:221], s[48:49], 0, v[128:129]
	s_mov_b32 m0, s64
	s_nop 0
	global_load_lds_dwordx4 v[220:221], off
	s_waitcnt vmcnt(8)
	s_waitcnt lgkmcnt(0)
	s_nop 0
	s_setprio 1
	s_barrier
	v_mfma_f32_16x16x32_bf16 v[124:127], v[150:153], v[182:185], v[124:127]
	v_mfma_f32_16x16x32_bf16 v[120:123], v[158:161], v[182:185], v[120:123]
	v_mfma_f32_16x16x32_bf16 v[108:111], v[150:153], v[190:193], v[108:111]
	v_mfma_f32_16x16x32_bf16 v[104:107], v[158:161], v[190:193], v[104:107]
	v_mfma_f32_16x16x32_bf16 v[92:95], v[150:153], v[198:201], v[92:95]
	v_mfma_f32_16x16x32_bf16 v[88:91], v[158:161], v[198:201], v[88:91]
	v_mfma_f32_16x16x32_bf16 v[76:79], v[150:153], v[206:209], v[76:79]
	v_mfma_f32_16x16x32_bf16 v[72:75], v[158:161], v[206:209], v[72:75]
	v_mfma_f32_16x16x32_bf16 v[124:127], v[154:157], v[186:189], v[124:127]
	v_mfma_f32_16x16x32_bf16 v[120:123], v[162:165], v[186:189], v[120:123]
	v_mfma_f32_16x16x32_bf16 v[108:111], v[154:157], v[194:197], v[108:111]
	v_mfma_f32_16x16x32_bf16 v[104:107], v[162:165], v[194:197], v[104:107]
	v_mfma_f32_16x16x32_bf16 v[92:95], v[154:157], v[202:205], v[92:95]
	v_mfma_f32_16x16x32_bf16 v[88:91], v[162:165], v[202:205], v[88:91]
	v_mfma_f32_16x16x32_bf16 v[76:79], v[154:157], v[210:213], v[76:79]
	v_mfma_f32_16x16x32_bf16 v[72:75], v[162:165], v[210:213], v[72:75]
	v_mfma_f32_16x16x32_bf16 v[116:119], v[166:169], v[182:185], v[116:119]
	v_mfma_f32_16x16x32_bf16 v[112:115], v[174:177], v[182:185], v[112:115]
	v_mfma_f32_16x16x32_bf16 v[100:103], v[166:169], v[190:193], v[100:103]
	v_mfma_f32_16x16x32_bf16 v[96:99], v[174:177], v[190:193], v[96:99]
	v_mfma_f32_16x16x32_bf16 v[84:87], v[166:169], v[198:201], v[84:87]
	v_mfma_f32_16x16x32_bf16 v[80:83], v[174:177], v[198:201], v[80:83]
	v_mfma_f32_16x16x32_bf16 v[68:71], v[166:169], v[206:209], v[68:71]
	v_mfma_f32_16x16x32_bf16 v[64:67], v[174:177], v[206:209], v[64:67]
	v_mfma_f32_16x16x32_bf16 v[116:119], v[170:173], v[186:189], v[116:119]
	v_mfma_f32_16x16x32_bf16 v[112:115], v[178:181], v[186:189], v[112:115]
	v_mfma_f32_16x16x32_bf16 v[100:103], v[170:173], v[194:197], v[100:103]
	v_mfma_f32_16x16x32_bf16 v[96:99], v[178:181], v[194:197], v[96:99]
	v_mfma_f32_16x16x32_bf16 v[84:87], v[170:173], v[202:205], v[84:87]
	v_mfma_f32_16x16x32_bf16 v[80:83], v[178:181], v[202:205], v[80:83]
	v_mfma_f32_16x16x32_bf16 v[68:71], v[170:173], v[210:213], v[68:71]
	v_mfma_f32_16x16x32_bf16 v[64:67], v[178:181], v[210:213], v[64:67]
	s_barrier
	s_setprio 0
	s_mov_b32 m0, s87
	v_lshl_add_u64 v[138:139], v[138:139], 0, s[16:17]
	ds_read_b128 v[182:185], v146 offset:49152
	ds_read_b128 v[186:189], v146 offset:50176
	ds_read_b128 v[190:193], v146 offset:51200
	ds_read_b128 v[194:197], v146 offset:52224
	ds_read_b128 v[198:201], v146 offset:53248
	ds_read_b128 v[202:205], v146 offset:54272
	ds_read_b128 v[206:209], v146 offset:55296
	ds_read_b128 v[210:213], v146 offset:56320
	global_load_lds_dwordx4 v[138:139], off
	v_lshl_add_u64 v[138:139], v[214:215], 0, s[16:17]
	s_mov_b32 m0, s85
	s_nop 0
	global_load_lds_dwordx4 v[138:139], off
	v_lshl_add_u64 v[138:139], s[46:47], 0, v[130:131]
	s_mov_b32 m0, s86
	s_nop 0
	global_load_lds_dwordx4 v[138:139], off
	v_lshl_add_u64 v[138:139], s[46:47], 0, v[128:129]
	s_mov_b32 m0, s84
	s_nop 0
	global_load_lds_dwordx4 v[138:139], off
	v_lshl_add_u64 v[138:139], v[216:217], 0, s[16:17]
	s_mov_b32 m0, s70
	s_nop 0
	global_load_lds_dwordx4 v[138:139], off
	v_lshl_add_u64 v[138:139], v[218:219], 0, s[16:17]
	s_mov_b32 m0, s71
	s_nop 0
	global_load_lds_dwordx4 v[138:139], off
	s_waitcnt vmcnt(8)
	s_waitcnt lgkmcnt(0)
	s_nop 0
	s_setprio 1
	s_barrier
	v_mfma_f32_16x16x32_bf16 v[60:63], v[150:153], v[182:185], v[60:63]
	v_mfma_f32_16x16x32_bf16 v[56:59], v[158:161], v[182:185], v[56:59]
	v_mfma_f32_16x16x32_bf16 v[44:47], v[150:153], v[190:193], v[44:47]
	v_mfma_f32_16x16x32_bf16 v[40:43], v[158:161], v[190:193], v[40:43]
	v_mfma_f32_16x16x32_bf16 v[28:31], v[150:153], v[198:201], v[28:31]
	v_mfma_f32_16x16x32_bf16 v[24:27], v[158:161], v[198:201], v[24:27]
	v_mfma_f32_16x16x32_bf16 v[12:15], v[150:153], v[206:209], v[12:15]
	v_mfma_f32_16x16x32_bf16 v[8:11], v[158:161], v[206:209], v[8:11]
	v_mfma_f32_16x16x32_bf16 v[60:63], v[154:157], v[186:189], v[60:63]
	v_mfma_f32_16x16x32_bf16 v[56:59], v[162:165], v[186:189], v[56:59]
	v_mfma_f32_16x16x32_bf16 v[44:47], v[154:157], v[194:197], v[44:47]
	v_mfma_f32_16x16x32_bf16 v[40:43], v[162:165], v[194:197], v[40:43]
	v_mfma_f32_16x16x32_bf16 v[28:31], v[154:157], v[202:205], v[28:31]
	v_mfma_f32_16x16x32_bf16 v[24:27], v[162:165], v[202:205], v[24:27]
	v_mfma_f32_16x16x32_bf16 v[12:15], v[154:157], v[210:213], v[12:15]
	v_mfma_f32_16x16x32_bf16 v[8:11], v[162:165], v[210:213], v[8:11]
	v_mfma_f32_16x16x32_bf16 v[52:55], v[166:169], v[182:185], v[52:55]
	v_mfma_f32_16x16x32_bf16 v[48:51], v[174:177], v[182:185], v[48:51]
	v_mfma_f32_16x16x32_bf16 v[36:39], v[166:169], v[190:193], v[36:39]
	v_mfma_f32_16x16x32_bf16 v[32:35], v[174:177], v[190:193], v[32:35]
	v_mfma_f32_16x16x32_bf16 v[20:23], v[166:169], v[198:201], v[20:23]
	v_mfma_f32_16x16x32_bf16 v[16:19], v[174:177], v[198:201], v[16:19]
	v_mfma_f32_16x16x32_bf16 v[4:7], v[166:169], v[206:209], v[4:7]
	v_mfma_f32_16x16x32_bf16 v[0:3], v[174:177], v[206:209], v[0:3]
	v_mfma_f32_16x16x32_bf16 v[52:55], v[170:173], v[186:189], v[52:55]
	v_mfma_f32_16x16x32_bf16 v[48:51], v[178:181], v[186:189], v[48:51]
	v_mfma_f32_16x16x32_bf16 v[36:39], v[170:173], v[194:197], v[36:39]
	v_mfma_f32_16x16x32_bf16 v[32:35], v[178:181], v[194:197], v[32:35]
	v_mfma_f32_16x16x32_bf16 v[20:23], v[170:173], v[202:205], v[20:23]
	v_mfma_f32_16x16x32_bf16 v[16:19], v[178:181], v[202:205], v[16:19]
	v_mfma_f32_16x16x32_bf16 v[4:7], v[170:173], v[210:213], v[4:7]
	v_mfma_f32_16x16x32_bf16 v[0:3], v[178:181], v[210:213], v[0:3]
	s_barrier
	s_setprio 0
	s_andn2_b64 vcc, exec, s[44:45]
	s_mov_b64 s[46:47], -1
	s_mov_b64 s[44:45], 0
	s_mov_b64 s[48:49], 0x100
	s_cbranch_vccz .LBB0_744
	s_and_b64 vcc, exec, s[20:21]
	s_cbranch_vccz .LBB0_747
	s_barrier

.LBB0_771:
	ds_read_b128 v[84:87], v208
	ds_read_b128 v[100:103], v208 offset:1024
	ds_read_b128 v[120:123], v208 offset:2048
	ds_read_b128 v[140:143], v208 offset:3072
	ds_read_b128 v[144:147], v209
	ds_read_b128 v[148:151], v209 offset:1024
	ds_read_b128 v[152:155], v209 offset:2048
	ds_read_b128 v[170:173], v209 offset:3072
	s_add_u32 s6, s8, 0x100
	s_addc_u32 s7, s9, 0
	s_cmp_eq_u32 s83, 2
	s_cselect_b32 s41, s35, s7
	s_cselect_b32 s40, s34, s6
	s_cselect_b32 s39, s37, s82
	s_cselect_b32 s38, s36, s81
	v_lshl_add_u64 v[214:215], s[8:9], 0, v[162:163]
	s_add_i32 m0, s42, 0xc000
	ds_read_b128 v[174:177], v210
	ds_read_b128 v[178:181], v210 offset:1024
	ds_read_b128 v[182:185], v210 offset:2048
	ds_read_b128 v[186:189], v210 offset:3072
	ds_read_b128 v[190:193], v210 offset:4096
	ds_read_b128 v[194:197], v210 offset:5120
	ds_read_b128 v[198:201], v210 offset:6144
	ds_read_b128 v[202:205], v210 offset:7168
	global_load_lds_dwordx4 v[214:215], off
	v_lshl_add_u64 v[214:215], s[8:9], 0, v[164:165]
	s_add_i32 m0, s42, 0xe000
	s_nop 0
	global_load_lds_dwordx4 v[214:215], off
	s_waitcnt vmcnt(8)
	s_waitcnt lgkmcnt(0)
	s_setprio 1
	s_barrier
	v_mfma_f32_16x16x32_bf16 v[136:139], v[84:87], v[174:177], v[136:139]
	v_mfma_f32_16x16x32_bf16 v[132:135], v[120:123], v[174:177], v[132:135]
	v_mfma_f32_16x16x32_bf16 v[116:119], v[84:87], v[182:185], v[116:119]
	v_mfma_f32_16x16x32_bf16 v[112:115], v[120:123], v[182:185], v[112:115]
	v_mfma_f32_16x16x32_bf16 v[96:99], v[84:87], v[190:193], v[96:99]
	v_mfma_f32_16x16x32_bf16 v[92:95], v[120:123], v[190:193], v[92:95]
	v_mfma_f32_16x16x32_bf16 v[76:79], v[84:87], v[198:201], v[76:79]
	v_mfma_f32_16x16x32_bf16 v[72:75], v[120:123], v[198:201], v[72:75]
	v_mfma_f32_16x16x32_bf16 v[136:139], v[100:103], v[178:181], v[136:139]
	v_mfma_f32_16x16x32_bf16 v[132:135], v[140:143], v[178:181], v[132:135]
	v_mfma_f32_16x16x32_bf16 v[116:119], v[100:103], v[186:189], v[116:119]
	v_mfma_f32_16x16x32_bf16 v[112:115], v[140:143], v[186:189], v[112:115]
	v_mfma_f32_16x16x32_bf16 v[96:99], v[100:103], v[194:197], v[96:99]
	v_mfma_f32_16x16x32_bf16 v[92:95], v[140:143], v[194:197], v[92:95]
	v_mfma_f32_16x16x32_bf16 v[76:79], v[100:103], v[202:205], v[76:79]
	v_mfma_f32_16x16x32_bf16 v[72:75], v[140:143], v[202:205], v[72:75]
	v_mfma_f32_16x16x32_bf16 v[128:131], v[144:147], v[174:177], v[128:131]
	v_mfma_f32_16x16x32_bf16 v[124:127], v[152:155], v[174:177], v[124:127]
	v_mfma_f32_16x16x32_bf16 v[108:111], v[144:147], v[182:185], v[108:111]
	v_mfma_f32_16x16x32_bf16 v[104:107], v[152:155], v[182:185], v[104:107]
	v_mfma_f32_16x16x32_bf16 v[88:91], v[144:147], v[190:193], v[88:91]
	v_mfma_f32_16x16x32_bf16 v[80:83], v[152:155], v[190:193], v[80:83]
	v_mfma_f32_16x16x32_bf16 v[68:71], v[144:147], v[198:201], v[68:71]
	v_mfma_f32_16x16x32_bf16 v[64:67], v[152:155], v[198:201], v[64:67]
	v_mfma_f32_16x16x32_bf16 v[128:131], v[148:151], v[178:181], v[128:131]
	v_mfma_f32_16x16x32_bf16 v[124:127], v[170:173], v[178:181], v[124:127]
	v_mfma_f32_16x16x32_bf16 v[108:111], v[148:151], v[186:189], v[108:111]
	v_mfma_f32_16x16x32_bf16 v[104:107], v[170:173], v[186:189], v[104:107]
	v_mfma_f32_16x16x32_bf16 v[88:91], v[148:151], v[194:197], v[88:91]
	v_mfma_f32_16x16x32_bf16 v[80:83], v[170:173], v[194:197], v[80:83]
	v_mfma_f32_16x16x32_bf16 v[68:71], v[148:151], v[202:205], v[68:71]
	v_mfma_f32_16x16x32_bf16 v[64:67], v[170:173], v[202:205], v[64:67]
	s_barrier
	s_setprio 0
	s_add_i32 s8, s61, s3
	v_lshl_add_u64 v[214:215], s[38:39], 0, v[156:157]
	s_mov_b32 m0, s8
	ds_read_b128 v[174:177], v210 offset:16384
	ds_read_b128 v[178:181], v210 offset:17408
	ds_read_b128 v[182:185], v210 offset:18432
	ds_read_b128 v[186:189], v210 offset:19456
	ds_read_b128 v[190:193], v210 offset:20480
	ds_read_b128 v[194:197], v210 offset:21504
	ds_read_b128 v[198:201], v210 offset:22528
	ds_read_b128 v[202:205], v210 offset:23552
	global_load_lds_dwordx4 v[214:215], off
	s_add_i32 m0, s8, 0x2000
	s_add_u32 s8, s38, 0x18000
	v_lshl_add_u64 v[216:217], s[38:39], 0, v[158:159]
	s_addc_u32 s9, s39, 0
	s_add_i32 s84, s62, s3
	global_load_lds_dwordx4 v[216:217], off
	v_lshl_add_u64 v[218:219], s[8:9], 0, v[156:157]
	s_mov_b32 m0, s84
	v_lshl_add_u64 v[220:221], s[40:41], 0, v[158:159]
	global_load_lds_dwordx4 v[218:219], off
	v_lshl_add_u64 v[218:219], s[8:9], 0, v[158:159]
	s_add_i32 m0, s84, 0x2000
	s_nop 0
	global_load_lds_dwordx4 v[218:219], off
	v_lshl_add_u64 v[218:219], s[40:41], 0, v[156:157]
	s_mov_b32 m0, s42
	s_nop 0
	global_load_lds_dwordx4 v[218:219], off
	s_mov_b32 m0, s43
	s_nop 0
	global_load_lds_dwordx4 v[220:221], off
	s_waitcnt vmcnt(8)
	s_waitcnt lgkmcnt(0)
	s_setprio 1
	s_barrier
	v_mfma_f32_16x16x32_bf16 v[60:63], v[84:87], v[174:177], v[60:63]
	v_mfma_f32_16x16x32_bf16 v[56:59], v[120:123], v[174:177], v[56:59]
	v_mfma_f32_16x16x32_bf16 v[44:47], v[84:87], v[182:185], v[44:47]
	v_mfma_f32_16x16x32_bf16 v[40:43], v[120:123], v[182:185], v[40:43]
	v_mfma_f32_16x16x32_bf16 v[28:31], v[84:87], v[190:193], v[28:31]
	v_mfma_f32_16x16x32_bf16 v[24:27], v[120:123], v[190:193], v[24:27]
	v_mfma_f32_16x16x32_bf16 v[12:15], v[84:87], v[198:201], v[12:15]
	v_mfma_f32_16x16x32_bf16 v[8:11], v[120:123], v[198:201], v[8:11]
	v_mfma_f32_16x16x32_bf16 v[60:63], v[100:103], v[178:181], v[60:63]
	v_mfma_f32_16x16x32_bf16 v[56:59], v[140:143], v[178:181], v[56:59]
	v_mfma_f32_16x16x32_bf16 v[44:47], v[100:103], v[186:189], v[44:47]
	v_mfma_f32_16x16x32_bf16 v[40:43], v[140:143], v[186:189], v[40:43]
	v_mfma_f32_16x16x32_bf16 v[28:31], v[100:103], v[194:197], v[28:31]
	v_mfma_f32_16x16x32_bf16 v[24:27], v[140:143], v[194:197], v[24:27]
	v_mfma_f32_16x16x32_bf16 v[12:15], v[100:103], v[202:205], v[12:15]
	v_mfma_f32_16x16x32_bf16 v[8:11], v[140:143], v[202:205], v[8:11]
	v_mfma_f32_16x16x32_bf16 v[52:55], v[144:147], v[174:177], v[52:55]
	v_mfma_f32_16x16x32_bf16 v[48:51], v[152:155], v[174:177], v[48:51]
	v_mfma_f32_16x16x32_bf16 v[36:39], v[144:147], v[182:185], v[36:39]
	v_mfma_f32_16x16x32_bf16 v[32:35], v[152:155], v[182:185], v[32:35]
	v_mfma_f32_16x16x32_bf16 v[20:23], v[144:147], v[190:193], v[20:23]
	v_mfma_f32_16x16x32_bf16 v[16:19], v[152:155], v[190:193], v[16:19]
	v_mfma_f32_16x16x32_bf16 v[4:7], v[144:147], v[198:201], v[4:7]
	v_mfma_f32_16x16x32_bf16 v[0:3], v[152:155], v[198:201], v[0:3]
	v_mfma_f32_16x16x32_bf16 v[52:55], v[148:151], v[178:181], v[52:55]
	v_mfma_f32_16x16x32_bf16 v[48:51], v[170:173], v[178:181], v[48:51]
	v_mfma_f32_16x16x32_bf16 v[36:39], v[148:151], v[186:189], v[36:39]
	v_mfma_f32_16x16x32_bf16 v[32:35], v[170:173], v[186:189], v[32:35]
	v_mfma_f32_16x16x32_bf16 v[20:23], v[148:151], v[194:197], v[20:23]
	v_mfma_f32_16x16x32_bf16 v[16:19], v[170:173], v[194:197], v[16:19]
	v_mfma_f32_16x16x32_bf16 v[4:7], v[148:151], v[202:205], v[4:7]
	v_mfma_f32_16x16x32_bf16 v[0:3], v[170:173], v[202:205], v[0:3]
	s_barrier
	s_setprio 0
	s_add_i32 s84, 0, 0x18000
	s_add_i32 s85, 0, 0x1c000
	v_add_u32_e32 v140, s84, v207
	v_add_u32_e32 v160, s85, v207
	ds_read_b128 v[84:87], v140
	ds_read_b128 v[100:103], v140 offset:1024
	ds_read_b128 v[120:123], v140 offset:2048
	ds_read_b128 v[140:143], v140 offset:3072
	ds_read_b128 v[144:147], v160
	ds_read_b128 v[148:151], v160 offset:1024
	ds_read_b128 v[152:155], v160 offset:2048
	ds_read_b128 v[170:173], v160 offset:3072
	s_add_u32 s8, s40, 0x18000
	s_addc_u32 s9, s41, 0
	s_mov_b32 m0, s44
	v_lshl_add_u64 v[222:223], s[8:9], 0, v[156:157]
	ds_read_b128 v[174:177], v210 offset:32768
	ds_read_b128 v[178:181], v210 offset:33792
	ds_read_b128 v[182:185], v210 offset:34816
	ds_read_b128 v[186:189], v210 offset:35840
	ds_read_b128 v[190:193], v210 offset:36864
	ds_read_b128 v[194:197], v210 offset:37888
	ds_read_b128 v[198:201], v210 offset:38912
	ds_read_b128 v[202:205], v210 offset:39936
	global_load_lds_dwordx4 v[222:223], off
	v_lshl_add_u64 v[222:223], s[8:9], 0, v[158:159]
	s_mov_b32 m0, s45
	s_nop 0
	global_load_lds_dwordx4 v[222:223], off
	s_waitcnt vmcnt(8)
	s_waitcnt lgkmcnt(0)
	s_setprio 1
	s_barrier
	v_mfma_f32_16x16x32_bf16 v[136:139], v[84:87], v[174:177], v[136:139]
	v_mfma_f32_16x16x32_bf16 v[132:135], v[120:123], v[174:177], v[132:135]
	v_mfma_f32_16x16x32_bf16 v[116:119], v[84:87], v[182:185], v[116:119]
	v_mfma_f32_16x16x32_bf16 v[112:115], v[120:123], v[182:185], v[112:115]
	v_mfma_f32_16x16x32_bf16 v[96:99], v[84:87], v[190:193], v[96:99]
	v_mfma_f32_16x16x32_bf16 v[92:95], v[120:123], v[190:193], v[92:95]
	v_mfma_f32_16x16x32_bf16 v[76:79], v[84:87], v[198:201], v[76:79]
	v_mfma_f32_16x16x32_bf16 v[72:75], v[120:123], v[198:201], v[72:75]
	v_mfma_f32_16x16x32_bf16 v[136:139], v[100:103], v[178:181], v[136:139]
	v_mfma_f32_16x16x32_bf16 v[132:135], v[140:143], v[178:181], v[132:135]
	v_mfma_f32_16x16x32_bf16 v[116:119], v[100:103], v[186:189], v[116:119]
	v_mfma_f32_16x16x32_bf16 v[112:115], v[140:143], v[186:189], v[112:115]
	v_mfma_f32_16x16x32_bf16 v[96:99], v[100:103], v[194:197], v[96:99]
	v_mfma_f32_16x16x32_bf16 v[92:95], v[140:143], v[194:197], v[92:95]
	v_mfma_f32_16x16x32_bf16 v[76:79], v[100:103], v[202:205], v[76:79]
	v_mfma_f32_16x16x32_bf16 v[72:75], v[140:143], v[202:205], v[72:75]
	v_mfma_f32_16x16x32_bf16 v[128:131], v[144:147], v[174:177], v[128:131]
	v_mfma_f32_16x16x32_bf16 v[124:127], v[152:155], v[174:177], v[124:127]
	v_mfma_f32_16x16x32_bf16 v[108:111], v[144:147], v[182:185], v[108:111]
	v_mfma_f32_16x16x32_bf16 v[104:107], v[152:155], v[182:185], v[104:107]
	v_mfma_f32_16x16x32_bf16 v[88:91], v[144:147], v[190:193], v[88:91]
	v_mfma_f32_16x16x32_bf16 v[80:83], v[152:155], v[190:193], v[80:83]
	v_mfma_f32_16x16x32_bf16 v[68:71], v[144:147], v[198:201], v[68:71]
	v_mfma_f32_16x16x32_bf16 v[64:67], v[152:155], v[198:201], v[64:67]
	v_mfma_f32_16x16x32_bf16 v[128:131], v[148:151], v[178:181], v[128:131]
	v_mfma_f32_16x16x32_bf16 v[124:127], v[170:173], v[178:181], v[124:127]
	v_mfma_f32_16x16x32_bf16 v[108:111], v[148:151], v[186:189], v[108:111]
	v_mfma_f32_16x16x32_bf16 v[104:107], v[170:173], v[186:189], v[104:107]
	v_mfma_f32_16x16x32_bf16 v[88:91], v[148:151], v[194:197], v[88:91]
	v_mfma_f32_16x16x32_bf16 v[80:83], v[170:173], v[194:197], v[80:83]
	v_mfma_f32_16x16x32_bf16 v[68:71], v[148:151], v[202:205], v[68:71]
	v_mfma_f32_16x16x32_bf16 v[64:67], v[170:173], v[202:205], v[64:67]
	s_barrier
	s_setprio 0
	s_add_i32 s8, s84, s3
	v_lshl_add_u64 v[214:215], v[214:215], 0, s[20:21]
	s_mov_b32 m0, s8
	ds_read_b128 v[174:177], v210 offset:49152
	ds_read_b128 v[178:181], v210 offset:50176
	ds_read_b128 v[182:185], v210 offset:51200
	ds_read_b128 v[186:189], v210 offset:52224
	ds_read_b128 v[190:193], v210 offset:53248
	ds_read_b128 v[194:197], v210 offset:54272
	ds_read_b128 v[198:201], v210 offset:55296
	ds_read_b128 v[202:205], v210 offset:56320
	global_load_lds_dwordx4 v[214:215], off
	s_add_i32 m0, s8, 0x2000
	s_add_u32 s8, s38, 0x18080
	v_lshl_add_u64 v[214:215], v[216:217], 0, s[20:21]
	s_addc_u32 s9, s39, 0
	s_add_i32 s38, s85, s3
	global_load_lds_dwordx4 v[214:215], off
	v_lshl_add_u64 v[214:215], s[8:9], 0, v[156:157]
	s_mov_b32 m0, s38
	s_nop 0
	global_load_lds_dwordx4 v[214:215], off
	v_lshl_add_u64 v[214:215], s[8:9], 0, v[158:159]
	s_add_i32 m0, s38, 0x2000
	s_nop 0
	global_load_lds_dwordx4 v[214:215], off
	v_lshl_add_u64 v[214:215], v[218:219], 0, s[20:21]
	s_mov_b32 m0, s51
	s_nop 0
	global_load_lds_dwordx4 v[214:215], off
	v_lshl_add_u64 v[214:215], v[220:221], 0, s[20:21]
	s_mov_b32 m0, s52
	s_nop 0
	global_load_lds_dwordx4 v[214:215], off
	s_waitcnt vmcnt(8)
	s_waitcnt lgkmcnt(0)
	s_nop 0
	s_setprio 1
	s_barrier
	v_mfma_f32_16x16x32_bf16 v[60:63], v[84:87], v[174:177], v[60:63]
	v_mfma_f32_16x16x32_bf16 v[56:59], v[120:123], v[174:177], v[56:59]
	v_mfma_f32_16x16x32_bf16 v[44:47], v[84:87], v[182:185], v[44:47]
	v_mfma_f32_16x16x32_bf16 v[40:43], v[120:123], v[182:185], v[40:43]
	v_mfma_f32_16x16x32_bf16 v[28:31], v[84:87], v[190:193], v[28:31]
	v_mfma_f32_16x16x32_bf16 v[24:27], v[120:123], v[190:193], v[24:27]
	v_mfma_f32_16x16x32_bf16 v[12:15], v[84:87], v[198:201], v[12:15]
	v_mfma_f32_16x16x32_bf16 v[8:11], v[120:123], v[198:201], v[8:11]
	v_mfma_f32_16x16x32_bf16 v[60:63], v[100:103], v[178:181], v[60:63]
	v_mfma_f32_16x16x32_bf16 v[56:59], v[140:143], v[178:181], v[56:59]
	v_mfma_f32_16x16x32_bf16 v[44:47], v[100:103], v[186:189], v[44:47]
	v_mfma_f32_16x16x32_bf16 v[40:43], v[140:143], v[186:189], v[40:43]
	v_mfma_f32_16x16x32_bf16 v[28:31], v[100:103], v[194:197], v[28:31]
	v_mfma_f32_16x16x32_bf16 v[24:27], v[140:143], v[194:197], v[24:27]
	v_mfma_f32_16x16x32_bf16 v[12:15], v[100:103], v[202:205], v[12:15]
	v_mfma_f32_16x16x32_bf16 v[8:11], v[140:143], v[202:205], v[8:11]
	v_mfma_f32_16x16x32_bf16 v[52:55], v[144:147], v[174:177], v[52:55]
	v_mfma_f32_16x16x32_bf16 v[48:51], v[152:155], v[174:177], v[48:51]
	v_mfma_f32_16x16x32_bf16 v[36:39], v[144:147], v[182:185], v[36:39]
	v_mfma_f32_16x16x32_bf16 v[32:35], v[152:155], v[182:185], v[32:35]
	v_mfma_f32_16x16x32_bf16 v[20:23], v[144:147], v[190:193], v[20:23]
	v_mfma_f32_16x16x32_bf16 v[16:19], v[152:155], v[190:193], v[16:19]
	v_mfma_f32_16x16x32_bf16 v[4:7], v[144:147], v[198:201], v[4:7]
	v_mfma_f32_16x16x32_bf16 v[0:3], v[152:155], v[198:201], v[0:3]
	v_mfma_f32_16x16x32_bf16 v[52:55], v[148:151], v[178:181], v[52:55]
	v_mfma_f32_16x16x32_bf16 v[48:51], v[170:173], v[178:181], v[48:51]
	v_mfma_f32_16x16x32_bf16 v[36:39], v[148:151], v[186:189], v[36:39]
	v_mfma_f32_16x16x32_bf16 v[32:35], v[170:173], v[186:189], v[32:35]
	v_mfma_f32_16x16x32_bf16 v[20:23], v[148:151], v[194:197], v[20:23]
	v_mfma_f32_16x16x32_bf16 v[16:19], v[170:173], v[194:197], v[16:19]
	v_mfma_f32_16x16x32_bf16 v[4:7], v[148:151], v[202:205], v[4:7]
	v_mfma_f32_16x16x32_bf16 v[0:3], v[170:173], v[202:205], v[0:3]
	s_barrier
	s_setprio 0
	s_add_i32 s83, s83, 2
	s_add_u32 s81, s81, 0x100
	s_addc_u32 s82, s82, 0
	s_cmp_gt_u32 s83, 3
	s_mov_b64 s[8:9], s[6:7]
	s_cbranch_scc0 .LBB0_771
	s_and_b64 vcc, exec, s[30:31]
	s_cbranch_vccz .LBB0_774
	s_barrier

.LBB0_938:
	ds_read_b128 v[128:131], v175
	ds_read_b128 v[132:135], v175 offset:1024
	ds_read_b128 v[136:139], v175 offset:2048
	ds_read_b128 v[140:143], v175 offset:3072
	ds_read_b128 v[144:147], v176
	ds_read_b128 v[148:151], v176 offset:1024
	ds_read_b128 v[168:171], v176 offset:2048
	ds_read_b128 v[182:185], v176 offset:3072
	s_add_u32 s36, s6, 0xfffe0080
	s_addc_u32 s37, s7, -1
	s_cmp_eq_u32 s42, 4
	s_cselect_b32 s39, s9, s37
	s_cselect_b32 s38, s27, s36
	s_cselect_b32 s37, s23, s41
	s_cselect_b32 s36, s35, s40
	v_lshl_add_u64 v[218:219], s[6:7], 0, v[158:159]
	s_add_i32 m0, s48, 0xc000
	ds_read_b128 v[186:189], v177
	ds_read_b128 v[190:193], v177 offset:1024
	ds_read_b128 v[194:197], v177 offset:2048
	ds_read_b128 v[198:201], v177 offset:3072
	ds_read_b128 v[202:205], v177 offset:4096
	ds_read_b128 v[206:209], v177 offset:5120
	ds_read_b128 v[210:213], v177 offset:6144
	ds_read_b128 v[214:217], v177 offset:7168
	global_load_lds_dwordx4 v[218:219], off
	v_lshl_add_u64 v[218:219], s[6:7], 0, v[160:161]
	s_add_i32 m0, s48, 0xe000
	s_nop 0
	global_load_lds_dwordx4 v[218:219], off
	s_waitcnt vmcnt(8)
	s_waitcnt lgkmcnt(0)
	s_setprio 1
	s_barrier
	v_mfma_f32_16x16x32_bf16 v[124:127], v[128:131], v[186:189], v[124:127]
	v_mfma_f32_16x16x32_bf16 v[120:123], v[136:139], v[186:189], v[120:123]
	v_mfma_f32_16x16x32_bf16 v[112:115], v[128:131], v[194:197], v[112:115]
	v_mfma_f32_16x16x32_bf16 v[116:119], v[136:139], v[194:197], v[116:119]
	v_mfma_f32_16x16x32_bf16 v[96:99], v[128:131], v[202:205], v[96:99]
	v_mfma_f32_16x16x32_bf16 v[104:107], v[136:139], v[202:205], v[104:107]
	v_mfma_f32_16x16x32_bf16 v[76:79], v[128:131], v[210:213], v[76:79]
	v_mfma_f32_16x16x32_bf16 v[72:75], v[136:139], v[210:213], v[72:75]
	v_mfma_f32_16x16x32_bf16 v[124:127], v[132:135], v[190:193], v[124:127]
	v_mfma_f32_16x16x32_bf16 v[120:123], v[140:143], v[190:193], v[120:123]
	v_mfma_f32_16x16x32_bf16 v[112:115], v[132:135], v[198:201], v[112:115]
	v_mfma_f32_16x16x32_bf16 v[116:119], v[140:143], v[198:201], v[116:119]
	v_mfma_f32_16x16x32_bf16 v[96:99], v[132:135], v[206:209], v[96:99]
	v_mfma_f32_16x16x32_bf16 v[104:107], v[140:143], v[206:209], v[104:107]
	v_mfma_f32_16x16x32_bf16 v[76:79], v[132:135], v[214:217], v[76:79]
	v_mfma_f32_16x16x32_bf16 v[72:75], v[140:143], v[214:217], v[72:75]
	v_mfma_f32_16x16x32_bf16 v[108:111], v[144:147], v[186:189], v[108:111]
	v_mfma_f32_16x16x32_bf16 v[100:103], v[168:171], v[186:189], v[100:103]
	v_mfma_f32_16x16x32_bf16 v[88:91], v[144:147], v[194:197], v[88:91]
	v_mfma_f32_16x16x32_bf16 v[92:95], v[168:171], v[194:197], v[92:95]
	v_mfma_f32_16x16x32_bf16 v[84:87], v[144:147], v[202:205], v[84:87]
	v_mfma_f32_16x16x32_bf16 v[80:83], v[168:171], v[202:205], v[80:83]
	v_mfma_f32_16x16x32_bf16 v[68:71], v[144:147], v[210:213], v[68:71]
	v_mfma_f32_16x16x32_bf16 v[64:67], v[168:171], v[210:213], v[64:67]
	v_mfma_f32_16x16x32_bf16 v[108:111], v[148:151], v[190:193], v[108:111]
	v_mfma_f32_16x16x32_bf16 v[100:103], v[182:185], v[190:193], v[100:103]
	v_mfma_f32_16x16x32_bf16 v[88:91], v[148:151], v[198:201], v[88:91]
	v_mfma_f32_16x16x32_bf16 v[92:95], v[182:185], v[198:201], v[92:95]
	v_mfma_f32_16x16x32_bf16 v[84:87], v[148:151], v[206:209], v[84:87]
	v_mfma_f32_16x16x32_bf16 v[80:83], v[182:185], v[206:209], v[80:83]
	v_mfma_f32_16x16x32_bf16 v[68:71], v[148:151], v[214:217], v[68:71]
	v_mfma_f32_16x16x32_bf16 v[64:67], v[182:185], v[214:217], v[64:67]
	s_barrier
	s_setprio 0
	s_add_i32 s43, s72, s47
	v_lshl_add_u64 v[218:219], s[36:37], 0, v[152:153]
	s_mov_b32 m0, s43
	ds_read_b128 v[186:189], v177 offset:16384
	ds_read_b128 v[190:193], v177 offset:17408
	ds_read_b128 v[194:197], v177 offset:18432
	ds_read_b128 v[198:201], v177 offset:19456
	ds_read_b128 v[202:205], v177 offset:20480
	ds_read_b128 v[206:209], v177 offset:21504
	ds_read_b128 v[210:213], v177 offset:22528
	ds_read_b128 v[214:217], v177 offset:23552
	global_load_lds_dwordx4 v[218:219], off
	s_add_i32 m0, s43, 0x2000
	s_add_u32 s88, s36, 0x20000
	v_lshl_add_u64 v[220:221], s[36:37], 0, v[154:155]
	s_addc_u32 s89, s37, 0
	s_add_i32 s43, s73, s47
	global_load_lds_dwordx4 v[220:221], off
	v_lshl_add_u64 v[222:223], s[88:89], 0, v[152:153]
	s_mov_b32 m0, s43
	v_lshl_add_u64 v[224:225], s[38:39], 0, v[154:155]
	global_load_lds_dwordx4 v[222:223], off
	v_lshl_add_u64 v[222:223], s[88:89], 0, v[154:155]
	s_add_i32 m0, s43, 0x2000
	s_nop 0
	global_load_lds_dwordx4 v[222:223], off
	v_lshl_add_u64 v[222:223], s[38:39], 0, v[152:153]
	s_mov_b32 m0, s48
	s_nop 0
	global_load_lds_dwordx4 v[222:223], off
	s_mov_b32 m0, s49
	s_nop 0
	global_load_lds_dwordx4 v[224:225], off
	s_waitcnt vmcnt(8)
	s_waitcnt lgkmcnt(0)
	s_setprio 1
	s_barrier
	v_mfma_f32_16x16x32_bf16 v[60:63], v[128:131], v[186:189], v[60:63]
	v_mfma_f32_16x16x32_bf16 v[56:59], v[136:139], v[186:189], v[56:59]
	v_mfma_f32_16x16x32_bf16 v[44:47], v[128:131], v[194:197], v[44:47]
	v_mfma_f32_16x16x32_bf16 v[40:43], v[136:139], v[194:197], v[40:43]
	v_mfma_f32_16x16x32_bf16 v[28:31], v[128:131], v[202:205], v[28:31]
	v_mfma_f32_16x16x32_bf16 v[24:27], v[136:139], v[202:205], v[24:27]
	v_mfma_f32_16x16x32_bf16 v[12:15], v[128:131], v[210:213], v[12:15]
	v_mfma_f32_16x16x32_bf16 v[8:11], v[136:139], v[210:213], v[8:11]
	v_mfma_f32_16x16x32_bf16 v[60:63], v[132:135], v[190:193], v[60:63]
	v_mfma_f32_16x16x32_bf16 v[56:59], v[140:143], v[190:193], v[56:59]
	v_mfma_f32_16x16x32_bf16 v[44:47], v[132:135], v[198:201], v[44:47]
	v_mfma_f32_16x16x32_bf16 v[40:43], v[140:143], v[198:201], v[40:43]
	v_mfma_f32_16x16x32_bf16 v[28:31], v[132:135], v[206:209], v[28:31]
	v_mfma_f32_16x16x32_bf16 v[24:27], v[140:143], v[206:209], v[24:27]
	v_mfma_f32_16x16x32_bf16 v[12:15], v[132:135], v[214:217], v[12:15]
	v_mfma_f32_16x16x32_bf16 v[8:11], v[140:143], v[214:217], v[8:11]
	v_mfma_f32_16x16x32_bf16 v[52:55], v[144:147], v[186:189], v[52:55]
	v_mfma_f32_16x16x32_bf16 v[48:51], v[168:171], v[186:189], v[48:51]
	v_mfma_f32_16x16x32_bf16 v[36:39], v[144:147], v[194:197], v[36:39]
	v_mfma_f32_16x16x32_bf16 v[32:35], v[168:171], v[194:197], v[32:35]
	v_mfma_f32_16x16x32_bf16 v[20:23], v[144:147], v[202:205], v[20:23]
	v_mfma_f32_16x16x32_bf16 v[16:19], v[168:171], v[202:205], v[16:19]
	v_mfma_f32_16x16x32_bf16 v[4:7], v[144:147], v[210:213], v[4:7]
	v_mfma_f32_16x16x32_bf16 v[0:3], v[168:171], v[210:213], v[0:3]
	v_mfma_f32_16x16x32_bf16 v[52:55], v[148:151], v[190:193], v[52:55]
	v_mfma_f32_16x16x32_bf16 v[48:51], v[182:185], v[190:193], v[48:51]
	v_mfma_f32_16x16x32_bf16 v[36:39], v[148:151], v[198:201], v[36:39]
	v_mfma_f32_16x16x32_bf16 v[32:35], v[182:185], v[198:201], v[32:35]
	v_mfma_f32_16x16x32_bf16 v[20:23], v[148:151], v[206:209], v[20:23]
	v_mfma_f32_16x16x32_bf16 v[16:19], v[182:185], v[206:209], v[16:19]
	v_mfma_f32_16x16x32_bf16 v[4:7], v[148:151], v[214:217], v[4:7]
	v_mfma_f32_16x16x32_bf16 v[0:3], v[182:185], v[214:217], v[0:3]
	s_barrier
	s_setprio 0
	s_add_i32 s43, 0, 0x18000
	s_add_i32 s88, 0, 0x1c000
	v_add_u32_e32 v140, s43, v173
	v_add_u32_e32 v156, s88, v173
	ds_read_b128 v[128:131], v140
	ds_read_b128 v[132:135], v140 offset:1024
	ds_read_b128 v[136:139], v140 offset:2048
	ds_read_b128 v[140:143], v140 offset:3072
	ds_read_b128 v[144:147], v156
	ds_read_b128 v[148:151], v156 offset:1024
	ds_read_b128 v[168:171], v156 offset:2048
	ds_read_b128 v[182:185], v156 offset:3072
	s_add_u32 s38, s38, 0x20000
	s_addc_u32 s39, s39, 0
	s_mov_b32 m0, s50
	v_lshl_add_u64 v[226:227], s[38:39], 0, v[152:153]
	ds_read_b128 v[186:189], v177 offset:32768
	ds_read_b128 v[190:193], v177 offset:33792
	ds_read_b128 v[194:197], v177 offset:34816
	ds_read_b128 v[198:201], v177 offset:35840
	ds_read_b128 v[202:205], v177 offset:36864
	ds_read_b128 v[206:209], v177 offset:37888
	ds_read_b128 v[210:213], v177 offset:38912
	ds_read_b128 v[214:217], v177 offset:39936
	global_load_lds_dwordx4 v[226:227], off
	v_lshl_add_u64 v[226:227], s[38:39], 0, v[154:155]
	s_mov_b32 m0, s51
	s_nop 0
	global_load_lds_dwordx4 v[226:227], off
	s_waitcnt vmcnt(8)
	s_waitcnt lgkmcnt(0)
	s_setprio 1
	s_barrier
	v_mfma_f32_16x16x32_bf16 v[124:127], v[128:131], v[186:189], v[124:127]
	v_mfma_f32_16x16x32_bf16 v[120:123], v[136:139], v[186:189], v[120:123]
	v_mfma_f32_16x16x32_bf16 v[112:115], v[128:131], v[194:197], v[112:115]
	v_mfma_f32_16x16x32_bf16 v[116:119], v[136:139], v[194:197], v[116:119]
	v_mfma_f32_16x16x32_bf16 v[96:99], v[128:131], v[202:205], v[96:99]
	v_mfma_f32_16x16x32_bf16 v[104:107], v[136:139], v[202:205], v[104:107]
	v_mfma_f32_16x16x32_bf16 v[76:79], v[128:131], v[210:213], v[76:79]
	v_mfma_f32_16x16x32_bf16 v[72:75], v[136:139], v[210:213], v[72:75]
	v_mfma_f32_16x16x32_bf16 v[124:127], v[132:135], v[190:193], v[124:127]
	v_mfma_f32_16x16x32_bf16 v[120:123], v[140:143], v[190:193], v[120:123]
	v_mfma_f32_16x16x32_bf16 v[112:115], v[132:135], v[198:201], v[112:115]
	v_mfma_f32_16x16x32_bf16 v[116:119], v[140:143], v[198:201], v[116:119]
	v_mfma_f32_16x16x32_bf16 v[96:99], v[132:135], v[206:209], v[96:99]
	v_mfma_f32_16x16x32_bf16 v[104:107], v[140:143], v[206:209], v[104:107]
	v_mfma_f32_16x16x32_bf16 v[76:79], v[132:135], v[214:217], v[76:79]
	v_mfma_f32_16x16x32_bf16 v[72:75], v[140:143], v[214:217], v[72:75]
	v_mfma_f32_16x16x32_bf16 v[108:111], v[144:147], v[186:189], v[108:111]
	v_mfma_f32_16x16x32_bf16 v[100:103], v[168:171], v[186:189], v[100:103]
	v_mfma_f32_16x16x32_bf16 v[88:91], v[144:147], v[194:197], v[88:91]
	v_mfma_f32_16x16x32_bf16 v[92:95], v[168:171], v[194:197], v[92:95]
	v_mfma_f32_16x16x32_bf16 v[84:87], v[144:147], v[202:205], v[84:87]
	v_mfma_f32_16x16x32_bf16 v[80:83], v[168:171], v[202:205], v[80:83]
	v_mfma_f32_16x16x32_bf16 v[68:71], v[144:147], v[210:213], v[68:71]
	v_mfma_f32_16x16x32_bf16 v[64:67], v[168:171], v[210:213], v[64:67]
	v_mfma_f32_16x16x32_bf16 v[108:111], v[148:151], v[190:193], v[108:111]
	v_mfma_f32_16x16x32_bf16 v[100:103], v[182:185], v[190:193], v[100:103]
	v_mfma_f32_16x16x32_bf16 v[88:91], v[148:151], v[198:201], v[88:91]
	v_mfma_f32_16x16x32_bf16 v[92:95], v[182:185], v[198:201], v[92:95]
	v_mfma_f32_16x16x32_bf16 v[84:87], v[148:151], v[206:209], v[84:87]
	v_mfma_f32_16x16x32_bf16 v[80:83], v[182:185], v[206:209], v[80:83]
	v_mfma_f32_16x16x32_bf16 v[68:71], v[148:151], v[214:217], v[68:71]
	v_mfma_f32_16x16x32_bf16 v[64:67], v[182:185], v[214:217], v[64:67]
	s_barrier
	s_setprio 0
	s_add_i32 s38, s43, s47
	v_lshl_add_u64 v[218:219], v[218:219], 0, s[16:17]
	s_mov_b32 m0, s38
	ds_read_b128 v[186:189], v177 offset:49152
	ds_read_b128 v[190:193], v177 offset:50176
	ds_read_b128 v[194:197], v177 offset:51200
	ds_read_b128 v[198:201], v177 offset:52224
	ds_read_b128 v[202:205], v177 offset:53248
	ds_read_b128 v[206:209], v177 offset:54272
	ds_read_b128 v[210:213], v177 offset:55296
	ds_read_b128 v[214:217], v177 offset:56320
	global_load_lds_dwordx4 v[218:219], off
	s_add_i32 m0, s38, 0x2000
	s_add_u32 s36, s36, 0x20080
	v_lshl_add_u64 v[218:219], v[220:221], 0, s[16:17]
	s_addc_u32 s37, s37, 0
	s_add_i32 s38, s88, s47
	global_load_lds_dwordx4 v[218:219], off
	v_lshl_add_u64 v[218:219], s[36:37], 0, v[152:153]
	s_mov_b32 m0, s38
	s_nop 0
	global_load_lds_dwordx4 v[218:219], off
	v_lshl_add_u64 v[218:219], s[36:37], 0, v[154:155]
	s_add_i32 m0, s38, 0x2000
	s_nop 0
	global_load_lds_dwordx4 v[218:219], off
	v_lshl_add_u64 v[218:219], v[222:223], 0, s[16:17]
	s_mov_b32 m0, s61
	s_nop 0
	global_load_lds_dwordx4 v[218:219], off
	v_lshl_add_u64 v[218:219], v[224:225], 0, s[16:17]
	s_mov_b32 m0, s62
	s_nop 0
	global_load_lds_dwordx4 v[218:219], off
	s_waitcnt vmcnt(8)
	s_waitcnt lgkmcnt(0)
	s_nop 0
	s_setprio 1
	s_barrier
	v_mfma_f32_16x16x32_bf16 v[60:63], v[128:131], v[186:189], v[60:63]
	v_mfma_f32_16x16x32_bf16 v[56:59], v[136:139], v[186:189], v[56:59]
	v_mfma_f32_16x16x32_bf16 v[44:47], v[128:131], v[194:197], v[44:47]
	v_mfma_f32_16x16x32_bf16 v[40:43], v[136:139], v[194:197], v[40:43]
	v_mfma_f32_16x16x32_bf16 v[28:31], v[128:131], v[202:205], v[28:31]
	v_mfma_f32_16x16x32_bf16 v[24:27], v[136:139], v[202:205], v[24:27]
	v_mfma_f32_16x16x32_bf16 v[12:15], v[128:131], v[210:213], v[12:15]
	v_mfma_f32_16x16x32_bf16 v[8:11], v[136:139], v[210:213], v[8:11]
	v_mfma_f32_16x16x32_bf16 v[60:63], v[132:135], v[190:193], v[60:63]
	v_mfma_f32_16x16x32_bf16 v[56:59], v[140:143], v[190:193], v[56:59]
	v_mfma_f32_16x16x32_bf16 v[44:47], v[132:135], v[198:201], v[44:47]
	v_mfma_f32_16x16x32_bf16 v[40:43], v[140:143], v[198:201], v[40:43]
	v_mfma_f32_16x16x32_bf16 v[28:31], v[132:135], v[206:209], v[28:31]
	v_mfma_f32_16x16x32_bf16 v[24:27], v[140:143], v[206:209], v[24:27]
	v_mfma_f32_16x16x32_bf16 v[12:15], v[132:135], v[214:217], v[12:15]
	v_mfma_f32_16x16x32_bf16 v[8:11], v[140:143], v[214:217], v[8:11]
	v_mfma_f32_16x16x32_bf16 v[52:55], v[144:147], v[186:189], v[52:55]
	v_mfma_f32_16x16x32_bf16 v[48:51], v[168:171], v[186:189], v[48:51]
	v_mfma_f32_16x16x32_bf16 v[36:39], v[144:147], v[194:197], v[36:39]
	v_mfma_f32_16x16x32_bf16 v[32:35], v[168:171], v[194:197], v[32:35]
	v_mfma_f32_16x16x32_bf16 v[20:23], v[144:147], v[202:205], v[20:23]
	v_mfma_f32_16x16x32_bf16 v[16:19], v[168:171], v[202:205], v[16:19]
	v_mfma_f32_16x16x32_bf16 v[4:7], v[144:147], v[210:213], v[4:7]
	v_mfma_f32_16x16x32_bf16 v[0:3], v[168:171], v[210:213], v[0:3]
	v_mfma_f32_16x16x32_bf16 v[52:55], v[148:151], v[190:193], v[52:55]
	v_mfma_f32_16x16x32_bf16 v[48:51], v[182:185], v[190:193], v[48:51]
	v_mfma_f32_16x16x32_bf16 v[36:39], v[148:151], v[198:201], v[36:39]
	v_mfma_f32_16x16x32_bf16 v[32:35], v[182:185], v[198:201], v[32:35]
	v_mfma_f32_16x16x32_bf16 v[20:23], v[148:151], v[206:209], v[20:23]
	v_mfma_f32_16x16x32_bf16 v[16:19], v[182:185], v[206:209], v[16:19]
	v_mfma_f32_16x16x32_bf16 v[4:7], v[148:151], v[214:217], v[4:7]
	v_mfma_f32_16x16x32_bf16 v[0:3], v[182:185], v[214:217], v[0:3]
	s_barrier
	s_setprio 0
	s_add_i32 s42, s42, 2
	s_add_u32 s6, s6, 0x100
	s_addc_u32 s7, s7, 0
	s_add_u32 s40, s40, 0x100
	s_addc_u32 s41, s41, 0
	s_cmp_gt_u32 s42, 5
	s_cbranch_scc0 .LBB0_938
	s_and_b64 vcc, exec, s[18:19]
	s_cbranch_vccz .LBB0_941
	s_barrier
